# P5 ctx half tiles (layer 0 tail): fragment reads hoisted per barrier interval into free VGPR pool, on top of early global loads
# speedup vs baseline: 1.0078x; 1.0078x over previous
; #define MFMA32(a, b, c) __builtin_amdgcn_mfma_f32_32x32x16_bf16((a), (b), (c), 0, 0, 0)
; DI float sigmoidf_(float x) { return __builtin_amdgcn_rcpf(1.f + __expf(-x)); }
; #define GEMM_LOADG(kk) { const int ka_ = amode ? (((kk) >> 6) * 96) : (kk); \
;     _Pragma("unroll") for (int i = 0; i < 4; ++i) ra[i] = *(const u32x4*)(A + (size_t)(lr + 32 * i) * lda + ka_ + lk); \
;     _Pragma("unroll") for (int i = 0; i < 2 * NT; ++i) rb[i] = *(const u32x4*)(Bt + (size_t)(lr + 32 * i) * ldb + (kk) + lk); }
; #define GEMM_STORES(buf) { u16* As_ = S + (buf) * TILE; u16* Bs_ = As_ + 128 * LS; \
;     _Pragma("unroll") for (int i = 0; i < 4; ++i) *(u32x4*)(As_ + (lr + 32 * i) * LS + lk) = ra[i]; \
;     _Pragma("unroll") for (int i = 0; i < 2 * NT; ++i) *(u32x4*)(Bs_ + (lr + 32 * i) * LS + lk) = rb[i]; }
; template <int NT>
; DI void gemm_main_np(f32x16 (&acc)[2][NT], const u16* __restrict__ A, int lda, int amode, const u16* __restrict__ Bt,
;                   int ldb, int K, char* smem) {
;     ...
;   GEMM_LOADG(0)
;   __syncthreads();
;   GEMM_STORES(0)
;   if (K > 64) GEMM_LOADG(64)
;   __syncthreads();
;   for (int k0 = 0; k0 < K; k0 += 64) {
;     const int cur = (k0 >> 6) & 1;
;     if (k0 + 64 < K) {
;       GEMM_STORES(cur ^ 1)
;       if (k0 + 128 < K) GEMM_LOADG(k0 + 128)
;     }
;     const u16* As = S + cur * TILE;
;     const u16* Bs = As + 128 * LS;
; #pragma unroll
;     for (int s = 0; s < 4; ++s) {
;       bf16x8 a[2], b[NT];
; #pragma unroll
;       for (int i = 0; i < 2; ++i) a[i] = *(const bf16x8*)(As + (wm * 64 + i * 32 + l31) * LS + s * 16 + hh * 8);
; #pragma unroll
;       for (int j = 0; j < NT; ++j) b[j] = *(const bf16x8*)(Bs + (wn * 32 * NT + j * 32 + l31) * LS + s * 16 + hh * 8);
; #pragma unroll
;       for (int i = 0; i < 2; ++i)
; #pragma unroll
;         for (int j = 0; j < NT; ++j) acc[i][j] = MFMA32(a[i], b[j], acc[i][j]);
;     }
; DI void p5_merge_half(KP p, int u, int mt_off, char* smem) {
;     ...
;     gemm_main_np<1>(ay, A, lda, amode, W + W_BRA + (size_t)br * 1024 * 512 + (size_t)nt * 64 * 512, 512, 512, smem);
; #pragma unroll
;     for (int i = 0; i < 2; ++i)
; #pragma unroll
;       for (int r = 0; r < 16; ++r) out[i][0][r] += sigmoidf_(ag[i][0][r]) * ay[i][0][r];
.LBB0_1715:
	v_mov_b32_e32 v60, v0
	s_nop 0
	v_mul_f32_e32 v18, 0xbfb8aa3b, v18
	v_ashrrev_i32_e32 v58, 3, v60
	v_lshlrev_b32_e32 v34, 4, v60
	v_add_u32_e32 v38, 32, v58
	v_add_u32_e32 v42, 64, v58
	v_add_u32_e32 v46, 0x60, v58
	v_and_b32_e32 v198, 0x70, v34
	v_ashrrev_i32_e32 v59, 31, v58
	v_mad_i64_i32 v[34:35], s[2:3], s24, v58, 0
	v_mad_i64_i32 v[38:39], s[2:3], s24, v38, 0
	v_mad_i64_i32 v[42:43], s[2:3], s24, v42, 0
	v_mad_i64_i32 v[46:47], s[2:3], s24, v46, 0
	v_lshl_add_u64 v[126:127], s[22:23], 0, v[198:199]
	v_lshlrev_b64 v[128:129], 1, v[34:35]
	v_lshlrev_b64 v[50:51], 10, v[58:59]
	v_and_b32_e32 v52, 7, v60
	s_add_u32 s2, s6, s16
	v_lshl_add_u64 v[34:35], v[126:127], 0, v[128:129]
	v_lshlrev_b64 v[130:131], 1, v[38:39]
	v_lshl_or_b32 v50, v52, 4, v50
	s_addc_u32 s3, s7, s17
	global_load_dwordx4 v[34:37], v[34:35], off
	v_lshl_add_u64 v[38:39], v[126:127], 0, v[130:131]
	v_lshlrev_b64 v[132:133], 1, v[42:43]
	v_lshl_add_u64 v[54:55], s[2:3], 0, v[50:51]
	global_load_dwordx4 v[38:41], v[38:39], off
	v_lshl_add_u64 v[42:43], v[126:127], 0, v[132:133]
	v_lshlrev_b64 v[134:135], 1, v[46:47]
	v_add_co_u32_e32 v136, vcc, s33, v54
	global_load_dwordx4 v[42:45], v[42:43], off
	v_lshl_add_u64 v[46:47], v[126:127], 0, v[134:135]
	v_addc_co_u32_e32 v137, vcc, 0, v55, vcc
	s_mov_b32 s2, 0xdee8000
	global_load_dwordx4 v[46:49], v[46:47], off
	v_add_co_u32_e32 v138, vcc, s2, v54
	global_load_dwordx4 v[50:53], v[136:137], off
	s_nop 0
	v_addc_co_u32_e32 v139, vcc, 0, v55, vcc
	global_load_dwordx4 v[54:57], v[138:139], off
	v_mad_u64_u32 v[122:123], s[2:3], v58, s60, v[198:199]
	s_and_b64 s[2:3], s[18:19], exec
	s_movk_i32 s2, 0x80
	s_cselect_b32 s2, s2, 0xc0
	s_add_u32 s2, s22, s2
	s_addc_u32 s3, s23, 0
	s_barrier
	v_and_b32_e32 v59, 31, v60
	v_lshrrev_b32_e32 v60, 1, v60
	v_and_or_b32 v61, v60, s31, v59
	v_and_b32_e32 v58, 16, v60
	v_and_or_b32 v59, v60, 32, v59
	v_mad_u32_u24 v123, v59, s60, v58
	v_mul_f32_e32 v19, 0xbfb8aa3b, v19
	v_mul_f32_e32 v2, 0xbfb8aa3b, v2
	v_mul_f32_e32 v3, 0xbfb8aa3b, v3
	v_exp_f32_e32 v18, v18
	v_exp_f32_e32 v19, v19
	v_exp_f32_e32 v2, v2
	v_exp_f32_e32 v3, v3
	v_add_f32_e32 v18, 1.0, v18
	v_add_f32_e32 v19, 1.0, v19
	v_add_f32_e32 v2, 1.0, v2
	v_add_f32_e32 v3, 1.0, v3
	v_rcp_f32_e32 v18, v18
	v_rcp_f32_e32 v19, v19
	v_rcp_f32_e32 v2, v2
	v_rcp_f32_e32 v3, v3
	s_waitcnt vmcnt(5)
	ds_write_b128 v122, v[34:37]
	s_waitcnt vmcnt(4)
	ds_write_b128 v122, v[38:41] offset:4608
	s_waitcnt vmcnt(3)
	ds_write_b128 v122, v[42:45] offset:9216
	s_waitcnt vmcnt(2)
	ds_write_b128 v122, v[46:49] offset:13824
	s_waitcnt vmcnt(1)
	ds_write_b128 v122, v[50:53] offset:18432
	s_waitcnt vmcnt(0)
	ds_write_b128 v122, v[54:57] offset:23040
	v_lshl_add_u64 v[46:47], s[2:3], 0, v[198:199]
	v_lshl_add_u64 v[34:35], v[46:47], 0, v[128:129]
	v_lshl_add_u64 v[38:39], v[46:47], 0, v[130:131]
	v_lshl_add_u64 v[42:43], v[46:47], 0, v[132:133]
	v_lshl_add_u64 v[46:47], v[46:47], 0, v[134:135]
	global_load_dwordx4 v[34:37], v[34:35], off
	s_and_b64 s[2:3], s[18:19], exec
	global_load_dwordx4 v[38:41], v[38:39], off
	s_movk_i32 s2, 0x100
	global_load_dwordx4 v[42:45], v[42:43], off
	s_nop 0
	global_load_dwordx4 v[46:49], v[46:47], off
	s_nop 0
	global_load_dwordx4 v[50:53], v[136:137], off offset:128
	global_load_dwordx4 v[54:57], v[138:139], off offset:128
	s_cselect_b32 s40, s2, 0x180
	s_waitcnt lgkmcnt(0)
	s_barrier
	v_mad_u64_u32 v[124:125], s[2:3], v61, s60, v[58:59]
	s_movk_i32 s2, 0x240
	s_waitcnt vmcnt(5)
	ds_write_b128 v122, v[34:37] offset:27648
	s_waitcnt vmcnt(4)
	ds_write_b128 v122, v[38:41] offset:32256
	s_waitcnt vmcnt(3)
	ds_write_b128 v122, v[42:45] offset:36864
	s_waitcnt vmcnt(2)
	ds_write_b128 v122, v[46:49] offset:41472
	s_waitcnt vmcnt(1)
	ds_write_b128 v122, v[50:53] offset:46080
	s_waitcnt vmcnt(0)
	ds_write_b128 v122, v[54:57] offset:50688
	ds_read_b128 v[166:169], v124 offset:4608
	ds_read_b128 v[170:173], v124
	ds_read_b128 v[174:177], v124 offset:32
	ds_read_b128 v[178:181], v123 offset:18432
	ds_read_b128 v[182:185], v123 offset:18464
	ds_read_b128 v[186:189], v124 offset:4640
	ds_read_b128 v[190:193], v124 offset:64
	ds_read_b128 v[194:197], v124 offset:4672
	ds_read_b128 v[200:203], v123 offset:18496
	ds_read_b128 v[204:207], v124 offset:96
	ds_read_b128 v[208:211], v124 offset:4704
	ds_read_b128 v[224:227], v123 offset:18528
	v_lshl_add_u64 v[34:35], v[126:127], 0, s[40:41]
	v_lshl_add_u64 v[36:37], v[34:35], 0, v[128:129]
	global_load_dwordx4 v[66:69], v[36:37], off
	v_lshl_add_u64 v[36:37], v[34:35], 0, v[130:131]
	global_load_dwordx4 v[70:73], v[36:37], off
	v_lshl_add_u64 v[36:37], v[34:35], 0, v[132:133]
	v_lshl_add_u64 v[34:35], v[34:35], 0, v[134:135]
	global_load_dwordx4 v[74:77], v[36:37], off
	global_load_dwordx4 v[78:81], v[34:35], off
	global_load_dwordx4 v[82:85], v[136:137], off offset:256
	global_load_dwordx4 v[86:89], v[138:139], off offset:256
	s_waitcnt lgkmcnt(10)
	s_waitcnt lgkmcnt(8)
	v_mfma_f32_32x32x16_bf16 v[50:65], v[170:173], v[178:181], 0
	s_cselect_b32 s40, 0x180, s2
	s_movk_i32 s2, 0x280
	v_mfma_f32_32x32x16_bf16 v[34:49], v[166:169], v[178:181], 0
	s_waitcnt lgkmcnt(7)
	v_mfma_f32_32x32x16_bf16 v[50:65], v[174:177], v[182:185], v[50:65]
	s_waitcnt lgkmcnt(6)
	v_mfma_f32_32x32x16_bf16 v[34:49], v[186:189], v[182:185], v[34:49]
	s_waitcnt lgkmcnt(5)
	s_waitcnt lgkmcnt(3)
	v_mfma_f32_32x32x16_bf16 v[50:65], v[190:193], v[200:203], v[50:65]
	v_mfma_f32_32x32x16_bf16 v[34:49], v[194:197], v[200:203], v[34:49]
	s_waitcnt lgkmcnt(0)
	s_barrier
; #define MFMA32(a, b, c) __builtin_amdgcn_mfma_f32_32x32x16_bf16((a), (b), (c), 0, 0, 0)
; #define GEMM_LOADG(kk) { const int ka_ = amode ? (((kk) >> 6) * 96) : (kk); \
;     _Pragma("unroll") for (int i = 0; i < 4; ++i) ra[i] = *(const u32x4*)(A + (size_t)(lr + 32 * i) * lda + ka_ + lk); \
;     _Pragma("unroll") for (int i = 0; i < 2 * NT; ++i) rb[i] = *(const u32x4*)(Bt + (size_t)(lr + 32 * i) * ldb + (kk) + lk); }
; #define GEMM_STORES(buf) { u16* As_ = S + (buf) * TILE; u16* Bs_ = As_ + 128 * LS; \
;     _Pragma("unroll") for (int i = 0; i < 4; ++i) *(u32x4*)(As_ + (lr + 32 * i) * LS + lk) = ra[i]; \
;     _Pragma("unroll") for (int i = 0; i < 2 * NT; ++i) *(u32x4*)(Bs_ + (lr + 32 * i) * LS + lk) = rb[i]; }
; template <int NT>
; DI void gemm_main_np(f32x16 (&acc)[2][NT], const u16* __restrict__ A, int lda, int amode, const u16* __restrict__ Bt,
;                   int ldb, int K, char* smem) {
;     ...
;   for (int k0 = 0; k0 < K; k0 += 64) {
;     const int cur = (k0 >> 6) & 1;
;     if (k0 + 64 < K) {
;       GEMM_STORES(cur ^ 1)
;       if (k0 + 128 < K) GEMM_LOADG(k0 + 128)
;     }
;     const u16* As = S + cur * TILE;
;     const u16* Bs = As + 128 * LS;
; #pragma unroll
;     for (int s = 0; s < 4; ++s) {
;       bf16x8 a[2], b[NT];
; #pragma unroll
;       for (int i = 0; i < 2; ++i) a[i] = *(const bf16x8*)(As + (wm * 64 + i * 32 + l31) * LS + s * 16 + hh * 8);
; #pragma unroll
;       for (int j = 0; j < NT; ++j) b[j] = *(const bf16x8*)(Bs + (wn * 32 * NT + j * 32 + l31) * LS + s * 16 + hh * 8);
; #pragma unroll
;       for (int i = 0; i < 2; ++i)
; #pragma unroll
;         for (int j = 0; j < NT; ++j) acc[i][j] = MFMA32(a[i], b[j], acc[i][j]);
;     }
;     __syncthreads();
	s_waitcnt vmcnt(5)
	ds_write_b128 v122, v[66:69]
	s_waitcnt vmcnt(4)
	ds_write_b128 v122, v[70:73] offset:4608
	s_waitcnt vmcnt(3)
	ds_write_b128 v122, v[74:77] offset:9216
	s_waitcnt vmcnt(2)
	ds_write_b128 v122, v[78:81] offset:13824
	s_waitcnt vmcnt(1)
	ds_write_b128 v122, v[82:85] offset:18432
	s_waitcnt vmcnt(0)
	ds_write_b128 v122, v[86:89] offset:23040
	ds_read_b128 v[230:233], v124 offset:32256
	ds_read_b128 v[236:239], v124 offset:27648
	ds_read_b128 v[244:247], v124 offset:27680
	ds_read_b128 v[248:251], v123 offset:46080
	ds_read_b128 v[170:173], v123 offset:46112
	ds_read_b128 v[166:169], v124 offset:32288
	ds_read_b128 v[178:181], v124 offset:27712
	ds_read_b128 v[174:177], v124 offset:32320
	ds_read_b128 v[186:189], v123 offset:46144
	ds_read_b128 v[182:185], v124 offset:27744
	ds_read_b128 v[190:193], v124 offset:32352
	ds_read_b128 v[194:197], v123 offset:46176
	v_lshl_add_u64 v[78:79], v[126:127], 0, s[40:41]
	v_lshl_add_u64 v[66:67], v[78:79], 0, v[128:129]
	v_lshl_add_u64 v[70:71], v[78:79], 0, v[130:131]
	v_lshl_add_u64 v[74:75], v[78:79], 0, v[132:133]
	v_lshl_add_u64 v[78:79], v[78:79], 0, v[134:135]
	global_load_dwordx4 v[66:69], v[66:67], off
	v_mfma_f32_32x32x16_bf16 v[34:49], v[208:211], v[224:227], v[34:49]
	global_load_dwordx4 v[70:73], v[70:71], off
	s_cselect_b32 s40, 0x200, s48
	global_load_dwordx4 v[74:77], v[74:75], off
	s_nop 0
	global_load_dwordx4 v[78:81], v[78:79], off
	s_nop 0
	global_load_dwordx4 v[82:85], v[136:137], off offset:384
	global_load_dwordx4 v[86:89], v[138:139], off offset:384
	v_mfma_f32_32x32x16_bf16 v[50:65], v[204:207], v[224:227], v[50:65]
	s_waitcnt lgkmcnt(11)
	s_waitcnt lgkmcnt(8)
	v_mfma_f32_32x32x16_bf16 v[34:49], v[230:233], v[248:251], v[34:49]
	v_mfma_f32_32x32x16_bf16 v[50:65], v[236:239], v[248:251], v[50:65]
	s_waitcnt lgkmcnt(7)
	v_mfma_f32_32x32x16_bf16 v[50:65], v[244:247], v[170:173], v[50:65]
	s_waitcnt lgkmcnt(6)
	v_mfma_f32_32x32x16_bf16 v[34:49], v[166:169], v[170:173], v[34:49]
	s_waitcnt lgkmcnt(5)
	s_waitcnt lgkmcnt(3)
	v_mfma_f32_32x32x16_bf16 v[50:65], v[178:181], v[186:189], v[50:65]
	v_mfma_f32_32x32x16_bf16 v[34:49], v[174:177], v[186:189], v[34:49]
	s_waitcnt lgkmcnt(0)
	s_barrier
	s_waitcnt vmcnt(5)
	ds_write_b128 v122, v[66:69] offset:27648
	s_waitcnt vmcnt(4)
	ds_write_b128 v122, v[70:73] offset:32256
	s_waitcnt vmcnt(3)
	ds_write_b128 v122, v[74:77] offset:36864
	s_waitcnt vmcnt(2)
	ds_write_b128 v122, v[78:81] offset:41472
	s_waitcnt vmcnt(1)
	ds_write_b128 v122, v[82:85] offset:46080
	s_waitcnt vmcnt(0)
	ds_write_b128 v122, v[86:89] offset:50688
	ds_read_b128 v[200:203], v124 offset:4608
	ds_read_b128 v[208:211], v124
	ds_read_b128 v[204:207], v124 offset:32
	ds_read_b128 v[224:227], v123 offset:18432
	ds_read_b128 v[230:233], v123 offset:18464
	ds_read_b128 v[236:239], v124 offset:4640
	ds_read_b128 v[248:251], v124 offset:64
	ds_read_b128 v[244:247], v124 offset:4672
	ds_read_b128 v[166:169], v123 offset:18496
	ds_read_b128 v[170:173], v124 offset:96
	ds_read_b128 v[178:181], v124 offset:4704
	ds_read_b128 v[174:177], v123 offset:18528
	v_lshl_add_u64 v[78:79], v[126:127], 0, s[40:41]
	v_lshl_add_u64 v[66:67], v[78:79], 0, v[128:129]
	v_lshl_add_u64 v[70:71], v[78:79], 0, v[130:131]
	v_lshl_add_u64 v[74:75], v[78:79], 0, v[132:133]
	v_lshl_add_u64 v[78:79], v[78:79], 0, v[134:135]
	global_load_dwordx4 v[66:69], v[66:67], off
	v_mfma_f32_32x32x16_bf16 v[34:49], v[190:193], v[194:197], v[34:49]
	global_load_dwordx4 v[70:73], v[70:71], off
	s_cselect_b32 s40, s2, 0x3c0
	global_load_dwordx4 v[74:77], v[74:75], off
	s_nop 0
	global_load_dwordx4 v[78:81], v[78:79], off
	s_nop 0
	global_load_dwordx4 v[82:85], v[136:137], off offset:512
	global_load_dwordx4 v[86:89], v[138:139], off offset:512
	s_movk_i32 s2, 0x480
	v_mfma_f32_32x32x16_bf16 v[50:65], v[182:185], v[194:197], v[50:65]
	s_waitcnt lgkmcnt(11)
	s_waitcnt lgkmcnt(8)
	v_mfma_f32_32x32x16_bf16 v[34:49], v[200:203], v[224:227], v[34:49]
	v_mfma_f32_32x32x16_bf16 v[50:65], v[208:211], v[224:227], v[50:65]
	s_waitcnt lgkmcnt(7)
	v_mfma_f32_32x32x16_bf16 v[50:65], v[204:207], v[230:233], v[50:65]
	s_waitcnt lgkmcnt(6)
	v_mfma_f32_32x32x16_bf16 v[34:49], v[236:239], v[230:233], v[34:49]
	s_waitcnt lgkmcnt(5)
	s_waitcnt lgkmcnt(3)
	v_mfma_f32_32x32x16_bf16 v[50:65], v[248:251], v[166:169], v[50:65]
	v_mfma_f32_32x32x16_bf16 v[34:49], v[244:247], v[166:169], v[34:49]
	s_waitcnt lgkmcnt(0)
	s_barrier
	s_waitcnt vmcnt(5)
	ds_write_b128 v122, v[66:69]
	s_waitcnt vmcnt(4)
	ds_write_b128 v122, v[70:73] offset:4608
	s_waitcnt vmcnt(3)
	ds_write_b128 v122, v[74:77] offset:9216
	s_waitcnt vmcnt(2)
	ds_write_b128 v122, v[78:81] offset:13824
	s_waitcnt vmcnt(1)
	ds_write_b128 v122, v[82:85] offset:18432
	s_waitcnt vmcnt(0)
	ds_write_b128 v122, v[86:89] offset:23040
	ds_read_b128 v[186:189], v124 offset:32256
	ds_read_b128 v[190:193], v124 offset:27648
	ds_read_b128 v[182:185], v124 offset:27680
	ds_read_b128 v[194:197], v123 offset:46080
	ds_read_b128 v[200:203], v123 offset:46112
	ds_read_b128 v[208:211], v124 offset:32288
	ds_read_b128 v[224:227], v124 offset:27712
	ds_read_b128 v[204:207], v124 offset:32320
	ds_read_b128 v[236:239], v123 offset:46144
	ds_read_b128 v[230:233], v124 offset:27744
	ds_read_b128 v[248:251], v124 offset:32352
	ds_read_b128 v[244:247], v123 offset:46176
	v_lshl_add_u64 v[78:79], v[126:127], 0, s[40:41]
	v_lshl_add_u64 v[66:67], v[78:79], 0, v[128:129]
	v_lshl_add_u64 v[70:71], v[78:79], 0, v[130:131]
	v_lshl_add_u64 v[74:75], v[78:79], 0, v[132:133]
	v_lshl_add_u64 v[78:79], v[78:79], 0, v[134:135]
	global_load_dwordx4 v[66:69], v[66:67], off
	v_mfma_f32_32x32x16_bf16 v[34:49], v[178:181], v[174:177], v[34:49]
	global_load_dwordx4 v[70:73], v[70:71], off
	s_cselect_b32 s40, 0x300, s2
	global_load_dwordx4 v[74:77], v[74:75], off
	s_nop 0
	global_load_dwordx4 v[78:81], v[78:79], off
	s_nop 0
	global_load_dwordx4 v[82:85], v[136:137], off offset:640
	global_load_dwordx4 v[86:89], v[138:139], off offset:640
	s_movk_i32 s2, 0x380
	v_mfma_f32_32x32x16_bf16 v[50:65], v[170:173], v[174:177], v[50:65]
	s_waitcnt lgkmcnt(11)
	s_waitcnt lgkmcnt(8)
	v_mfma_f32_32x32x16_bf16 v[34:49], v[186:189], v[194:197], v[34:49]
	v_mfma_f32_32x32x16_bf16 v[50:65], v[190:193], v[194:197], v[50:65]
	s_waitcnt lgkmcnt(7)
	v_mfma_f32_32x32x16_bf16 v[50:65], v[182:185], v[200:203], v[50:65]
	s_waitcnt lgkmcnt(6)
	v_mfma_f32_32x32x16_bf16 v[34:49], v[208:211], v[200:203], v[34:49]
	s_waitcnt lgkmcnt(5)
	s_waitcnt lgkmcnt(3)
	v_mfma_f32_32x32x16_bf16 v[50:65], v[224:227], v[236:239], v[50:65]
	v_mfma_f32_32x32x16_bf16 v[34:49], v[204:207], v[236:239], v[34:49]
	s_waitcnt lgkmcnt(0)
	s_barrier
; #define MFMA32(a, b, c) __builtin_amdgcn_mfma_f32_32x32x16_bf16((a), (b), (c), 0, 0, 0)
; #define GEMM_LOADG(kk) { const int ka_ = amode ? (((kk) >> 6) * 96) : (kk); \
;     _Pragma("unroll") for (int i = 0; i < 4; ++i) ra[i] = *(const u32x4*)(A + (size_t)(lr + 32 * i) * lda + ka_ + lk); \
;     _Pragma("unroll") for (int i = 0; i < 2 * NT; ++i) rb[i] = *(const u32x4*)(Bt + (size_t)(lr + 32 * i) * ldb + (kk) + lk); }
; template <int NT>
; DI void gemm_main_np(f32x16 (&acc)[2][NT], const u16* __restrict__ A, int lda, int amode, const u16* __restrict__ Bt,
;                   int ldb, int K, char* smem) {
;     ...
;   for (int k0 = 0; k0 < K; k0 += 64) {
;     const int cur = (k0 >> 6) & 1;
;     if (k0 + 64 < K) {
;       GEMM_STORES(cur ^ 1)
;       if (k0 + 128 < K) GEMM_LOADG(k0 + 128)
;     }
;     const u16* As = S + cur * TILE;
;     const u16* Bs = As + 128 * LS;
; #pragma unroll
;     for (int s = 0; s < 4; ++s) {
;       bf16x8 a[2], b[NT];
; #pragma unroll
;       for (int i = 0; i < 2; ++i) a[i] = *(const bf16x8*)(As + (wm * 64 + i * 32 + l31) * LS + s * 16 + hh * 8);
; #pragma unroll
;       for (int j = 0; j < NT; ++j) b[j] = *(const bf16x8*)(Bs + (wn * 32 * NT + j * 32 + l31) * LS + s * 16 + hh * 8);
; #pragma unroll
;       for (int i = 0; i < 2; ++i)
; #pragma unroll
;         for (int j = 0; j < NT; ++j) acc[i][j] = MFMA32(a[i], b[j], acc[i][j]);
;     }
;     __syncthreads();
; DI void p5_merge_half(KP p, int u, int mt_off, char* smem) {
;     ...
; #pragma unroll 1
;   for (int br = 0; br < 3; ++br) {
;     f32x16 ag[2][1], ay[2][1];
;     zero_acc(ag[0][0]); zero_acc(ag[1][0]); zero_acc(ay[0][0]); zero_acc(ay[1][0]);
;     gemm_main_np<1>(ag, H, 1024, 0, W + W_ING + (size_t)(br * 1024 + nt * 64) * 1024, 1024, 1024, smem);
;     const u16* A;
;     int lda, amode = 0;
;     if (br == 0) { A = (const u16*)(p->ws + OFF_Q) + (size_t)mt * 128 * 768; lda = 768; amode = 1; }
;     else if (br == 1) { A = (const u16*)(p->ws + OFF_ZLG) + (size_t)mt * 128 * 512; lda = 512; }
;     else { A = (const u16*)(p->ws + OFF_YC) + (size_t)mt * 128 * 512; lda = 512; }
;     gemm_main_np<1>(ay, A, lda, amode, W + W_BRA + (size_t)br * 1024 * 512 + (size_t)nt * 64 * 512, 512, 512, smem);
	s_waitcnt vmcnt(5)
	ds_write_b128 v122, v[66:69] offset:27648
	s_waitcnt vmcnt(4)
	ds_write_b128 v122, v[70:73] offset:32256
	s_waitcnt vmcnt(3)
	ds_write_b128 v122, v[74:77] offset:36864
	s_waitcnt vmcnt(2)
	ds_write_b128 v122, v[78:81] offset:41472
	s_waitcnt vmcnt(1)
	ds_write_b128 v122, v[82:85] offset:46080
	s_waitcnt vmcnt(0)
	ds_write_b128 v122, v[86:89] offset:50688
	ds_read_b128 v[166:169], v124 offset:4608
	ds_read_b128 v[178:181], v124
	ds_read_b128 v[170:173], v124 offset:32
	ds_read_b128 v[174:177], v123 offset:18432
	ds_read_b128 v[186:189], v123 offset:18464
	ds_read_b128 v[190:193], v124 offset:4640
	ds_read_b128 v[194:197], v124 offset:64
	ds_read_b128 v[182:185], v124 offset:4672
	ds_read_b128 v[208:211], v123 offset:18496
	ds_read_b128 v[200:203], v124 offset:96
	ds_read_b128 v[224:227], v124 offset:4704
	ds_read_b128 v[204:207], v123 offset:18528
	v_lshl_add_u64 v[78:79], v[126:127], 0, s[40:41]
	v_lshl_add_u64 v[66:67], v[78:79], 0, v[128:129]
	v_lshl_add_u64 v[70:71], v[78:79], 0, v[130:131]
	v_lshl_add_u64 v[74:75], v[78:79], 0, v[132:133]
	v_lshl_add_u64 v[78:79], v[78:79], 0, v[134:135]
	global_load_dwordx4 v[66:69], v[66:67], off
	v_mfma_f32_32x32x16_bf16 v[34:49], v[248:251], v[244:247], v[34:49]
	global_load_dwordx4 v[70:73], v[70:71], off
	s_cselect_b32 s40, s2, 0x540
	global_load_dwordx4 v[74:77], v[74:75], off
	s_nop 0
	global_load_dwordx4 v[78:81], v[78:79], off
	s_nop 0
	global_load_dwordx4 v[82:85], v[136:137], off offset:768
	global_load_dwordx4 v[86:89], v[138:139], off offset:768
	s_add_i32 s29, s29, 1
	s_add_u32 s16, s16, 0x100000
	s_addc_u32 s17, s17, 0
	v_mfma_f32_32x32x16_bf16 v[50:65], v[230:233], v[244:247], v[50:65]
	s_add_u32 s26, s26, 0x200000
	s_addc_u32 s27, s27, 0
	s_cmp_lg_u32 s29, 3
	s_waitcnt lgkmcnt(11)
	s_waitcnt lgkmcnt(8)
	v_mfma_f32_32x32x16_bf16 v[34:49], v[166:169], v[174:177], v[34:49]
	v_mfma_f32_32x32x16_bf16 v[50:65], v[178:181], v[174:177], v[50:65]
	s_waitcnt lgkmcnt(7)
	v_mfma_f32_32x32x16_bf16 v[50:65], v[170:173], v[186:189], v[50:65]
	s_waitcnt lgkmcnt(6)
	v_mfma_f32_32x32x16_bf16 v[34:49], v[190:193], v[186:189], v[34:49]
	s_waitcnt lgkmcnt(5)
	s_waitcnt lgkmcnt(3)
	v_mfma_f32_32x32x16_bf16 v[50:65], v[194:197], v[208:211], v[50:65]
	v_mfma_f32_32x32x16_bf16 v[34:49], v[182:185], v[208:211], v[34:49]
	s_waitcnt lgkmcnt(0)
	s_barrier
	s_waitcnt vmcnt(5)
	ds_write_b128 v122, v[66:69]
	s_waitcnt vmcnt(4)
	ds_write_b128 v122, v[70:73] offset:4608
	s_waitcnt vmcnt(3)
	ds_write_b128 v122, v[74:77] offset:9216
	s_waitcnt vmcnt(2)
	ds_write_b128 v122, v[78:81] offset:13824
	s_waitcnt vmcnt(1)
	ds_write_b128 v122, v[82:85] offset:18432
	s_waitcnt vmcnt(0)
	ds_write_b128 v122, v[86:89] offset:23040
	ds_read_b128 v[236:239], v124 offset:32256
	ds_read_b128 v[248:251], v124 offset:27648
	ds_read_b128 v[230:233], v124 offset:27680
	ds_read_b128 v[244:247], v123 offset:46080
	ds_read_b128 v[166:169], v123 offset:46112
	ds_read_b128 v[178:181], v124 offset:32288
	ds_read_b128 v[174:177], v124 offset:27712
	ds_read_b128 v[170:173], v124 offset:32320
	ds_read_b128 v[190:193], v123 offset:46144
	ds_read_b128 v[186:189], v124 offset:27744
	ds_read_b128 v[194:197], v124 offset:32352
	ds_read_b128 v[182:185], v123 offset:46176
	v_lshl_add_u64 v[78:79], v[126:127], 0, s[40:41]
	v_lshl_add_u64 v[66:67], v[78:79], 0, v[128:129]
	v_lshl_add_u64 v[70:71], v[78:79], 0, v[130:131]
	v_lshl_add_u64 v[74:75], v[78:79], 0, v[132:133]
	v_lshl_add_u64 v[78:79], v[78:79], 0, v[134:135]
	global_load_dwordx4 v[66:69], v[66:67], off
	v_mfma_f32_32x32x16_bf16 v[34:49], v[224:227], v[204:207], v[34:49]
	global_load_dwordx4 v[70:73], v[70:71], off
	s_nop 0
	global_load_dwordx4 v[74:77], v[74:75], off
	s_nop 0
	global_load_dwordx4 v[78:81], v[78:79], off
	s_nop 0
	global_load_dwordx4 v[82:85], v[136:137], off offset:896
	global_load_dwordx4 v[86:89], v[138:139], off offset:896
	v_mfma_f32_32x32x16_bf16 v[50:65], v[200:203], v[204:207], v[50:65]
	s_waitcnt lgkmcnt(11)
	s_waitcnt lgkmcnt(8)
	v_mfma_f32_32x32x16_bf16 v[34:49], v[236:239], v[244:247], v[34:49]
	v_mfma_f32_32x32x16_bf16 v[50:65], v[248:251], v[244:247], v[50:65]
	s_waitcnt lgkmcnt(6)
	v_mfma_f32_32x32x16_bf16 v[34:49], v[178:181], v[166:169], v[34:49]
	v_mfma_f32_32x32x16_bf16 v[50:65], v[230:233], v[166:169], v[50:65]
	s_waitcnt lgkmcnt(4)
	s_waitcnt lgkmcnt(3)
	v_mfma_f32_32x32x16_bf16 v[34:49], v[170:173], v[190:193], v[34:49]
	v_mfma_f32_32x32x16_bf16 v[50:65], v[174:177], v[190:193], v[50:65]
	s_waitcnt lgkmcnt(0)
	s_barrier
	s_waitcnt vmcnt(5)
	ds_write_b128 v122, v[66:69] offset:27648
	s_waitcnt vmcnt(4)
	ds_write_b128 v122, v[70:73] offset:32256
	s_waitcnt vmcnt(3)
	ds_write_b128 v122, v[74:77] offset:36864
	s_waitcnt vmcnt(2)
	ds_write_b128 v122, v[78:81] offset:41472
	s_waitcnt vmcnt(1)
	ds_write_b128 v122, v[82:85] offset:46080
	s_waitcnt vmcnt(0)
	ds_write_b128 v122, v[86:89] offset:50688
	ds_read_b128 v[208:211], v124 offset:4608
	ds_read_b128 v[224:227], v124
	ds_read_b128 v[200:203], v124 offset:32
	ds_read_b128 v[204:207], v123 offset:18432
	ds_read_b128 v[236:239], v123 offset:18464
	ds_read_b128 v[248:251], v124 offset:4640
	ds_read_b128 v[244:247], v124 offset:64
	ds_read_b128 v[178:181], v124 offset:4672
	ds_read_b128 v[230:233], v123 offset:18496
	ds_read_b128 v[166:169], v124 offset:96
	ds_read_b128 v[170:173], v124 offset:4704
	ds_read_b128 v[174:177], v123 offset:18528
	v_mfma_f32_32x32x16_bf16 v[34:49], v[194:197], v[182:185], v[34:49]
	v_mfma_f32_32x32x16_bf16 v[50:65], v[186:189], v[182:185], v[50:65]
	s_waitcnt lgkmcnt(11)
	s_waitcnt lgkmcnt(8)
	v_mfma_f32_32x32x16_bf16 v[34:49], v[208:211], v[204:207], v[34:49]
	v_mfma_f32_32x32x16_bf16 v[50:65], v[224:227], v[204:207], v[50:65]
	s_waitcnt lgkmcnt(7)
	v_mfma_f32_32x32x16_bf16 v[50:65], v[200:203], v[236:239], v[50:65]
	s_waitcnt lgkmcnt(6)
	v_mfma_f32_32x32x16_bf16 v[34:49], v[248:251], v[236:239], v[34:49]
	s_waitcnt lgkmcnt(5)
	s_waitcnt lgkmcnt(3)
	v_mfma_f32_32x32x16_bf16 v[50:65], v[244:247], v[230:233], v[50:65]
	v_mfma_f32_32x32x16_bf16 v[34:49], v[178:181], v[230:233], v[34:49]
	s_waitcnt lgkmcnt(0)
	s_barrier
; #define MFMA32(a, b, c) __builtin_amdgcn_mfma_f32_32x32x16_bf16((a), (b), (c), 0, 0, 0)
; DI float sigmoidf_(float x) { return __builtin_amdgcn_rcpf(1.f + __expf(-x)); }
; template <int NT>
; DI void gemm_main_np(f32x16 (&acc)[2][NT], const u16* __restrict__ A, int lda, int amode, const u16* __restrict__ Bt,
;                   int ldb, int K, char* smem) {
;     ...
; #pragma unroll
;     for (int s = 0; s < 4; ++s) {
;       bf16x8 a[2], b[NT];
; #pragma unroll
;       for (int i = 0; i < 2; ++i) a[i] = *(const bf16x8*)(As + (wm * 64 + i * 32 + l31) * LS + s * 16 + hh * 8);
; #pragma unroll
;       for (int j = 0; j < NT; ++j) b[j] = *(const bf16x8*)(Bs + (wn * 32 * NT + j * 32 + l31) * LS + s * 16 + hh * 8);
; #pragma unroll
;       for (int i = 0; i < 2; ++i)
; #pragma unroll
;         for (int j = 0; j < NT; ++j) acc[i][j] = MFMA32(a[i], b[j], acc[i][j]);
;     }
;     __syncthreads();
; DI void p5_merge_half(KP p, int u, int mt_off, char* smem) {
;     ...
; #pragma unroll
;     for (int i = 0; i < 2; ++i)
; #pragma unroll
;       for (int r = 0; r < 16; ++r) out[i][0][r] += sigmoidf_(ag[i][0][r]) * ay[i][0][r];
	ds_read_b128 v[190:193], v123 offset:46176
	ds_read_b128 v[194:197], v124 offset:32352
	ds_read_b128 v[186:189], v124 offset:27744
	ds_read_b128 v[182:185], v123 offset:46144
	ds_read_b128 v[208:211], v124 offset:32320
	ds_read_b128 v[224:227], v124 offset:27712
	ds_read_b128 v[204:207], v123 offset:46080
	ds_read_b128 v[200:203], v123 offset:46112
	ds_read_b128 v[248:251], v124 offset:32288
	ds_read_b128 v[236:239], v124 offset:27648
	ds_read_b128 v[244:247], v124 offset:27680
	ds_read_b128 v[178:181], v124 offset:32256
	v_mfma_f32_32x32x16_bf16 v[50:65], v[166:169], v[174:177], v[50:65]
	v_mfma_f32_32x32x16_bf16 v[34:49], v[170:173], v[174:177], v[34:49]
	s_waitcnt lgkmcnt(0)
	s_barrier
	v_mfma_f32_32x32x16_bf16 v[50:65], v[236:239], v[204:207], v[50:65]
	v_mfma_f32_32x32x16_bf16 v[34:49], v[178:181], v[204:207], v[34:49]
	v_mfma_f32_32x32x16_bf16 v[50:65], v[244:247], v[200:203], v[50:65]
	v_mfma_f32_32x32x16_bf16 v[34:49], v[248:251], v[200:203], v[34:49]
	v_mfma_f32_32x32x16_bf16 v[50:65], v[224:227], v[182:185], v[50:65]
	v_mfma_f32_32x32x16_bf16 v[34:49], v[208:211], v[182:185], v[34:49]
	v_mfma_f32_32x32x16_bf16 v[50:65], v[186:189], v[190:193], v[50:65]
	v_mfma_f32_32x32x16_bf16 v[34:49], v[194:197], v[190:193], v[34:49]
	s_nop 10
	v_fma_f32 v120, v18, v50, v120
	v_fma_f32 v121, v19, v51, v121
	v_mul_f32_e32 v18, 0xbfb8aa3b, v20
	v_mul_f32_e32 v19, 0xbfb8aa3b, v21
	v_exp_f32_e32 v18, v18
	v_exp_f32_e32 v19, v19
	v_pk_fma_f32 v[104:105], v[2:3], v[34:35], v[104:105]
	v_mul_f32_e32 v2, 0xbfb8aa3b, v4
	v_mul_f32_e32 v3, 0xbfb8aa3b, v5
	v_exp_f32_e32 v2, v2
	v_exp_f32_e32 v3, v3
	v_add_f32_e32 v18, 1.0, v18
	v_add_f32_e32 v19, 1.0, v19
	v_add_f32_e32 v2, 1.0, v2
	v_add_f32_e32 v3, 1.0, v3
	v_rcp_f32_e32 v18, v18
	v_rcp_f32_e32 v19, v19
	v_rcp_f32_e32 v2, v2
	v_rcp_f32_e32 v3, v3
	v_pk_fma_f32 v[118:119], v[18:19], v[52:53], v[118:119]
	v_mul_f32_e32 v18, 0xbfb8aa3b, v22
	v_mul_f32_e32 v19, 0xbfb8aa3b, v23
	v_pk_fma_f32 v[102:103], v[2:3], v[36:37], v[102:103]
	v_mul_f32_e32 v2, 0xbfb8aa3b, v6
	v_mul_f32_e32 v3, 0xbfb8aa3b, v7
	v_exp_f32_e32 v18, v18
	v_exp_f32_e32 v19, v19
	v_exp_f32_e32 v2, v2
	v_exp_f32_e32 v3, v3
	v_add_f32_e32 v18, 1.0, v18
	v_add_f32_e32 v19, 1.0, v19
	v_add_f32_e32 v2, 1.0, v2
	v_add_f32_e32 v3, 1.0, v3
	v_rcp_f32_e32 v18, v18
	v_rcp_f32_e32 v19, v19
	v_rcp_f32_e32 v2, v2
	v_rcp_f32_e32 v3, v3
	v_pk_fma_f32 v[116:117], v[18:19], v[54:55], v[116:117]
	v_mul_f32_e32 v18, 0xbfb8aa3b, v24
	v_mul_f32_e32 v19, 0xbfb8aa3b, v25
	v_pk_fma_f32 v[100:101], v[2:3], v[38:39], v[100:101]
	v_mul_f32_e32 v2, 0xbfb8aa3b, v8
	v_mul_f32_e32 v3, 0xbfb8aa3b, v9
	v_exp_f32_e32 v18, v18
	v_exp_f32_e32 v19, v19
	v_exp_f32_e32 v2, v2
	v_exp_f32_e32 v3, v3
	v_add_f32_e32 v18, 1.0, v18
	v_add_f32_e32 v19, 1.0, v19
	v_add_f32_e32 v2, 1.0, v2
	v_add_f32_e32 v3, 1.0, v3
	v_rcp_f32_e32 v18, v18
	v_rcp_f32_e32 v19, v19
	v_rcp_f32_e32 v2, v2
	v_rcp_f32_e32 v3, v3
	v_pk_fma_f32 v[114:115], v[18:19], v[56:57], v[114:115]
	v_mul_f32_e32 v18, 0xbfb8aa3b, v26
	v_mul_f32_e32 v19, 0xbfb8aa3b, v27
	v_pk_fma_f32 v[98:99], v[2:3], v[40:41], v[98:99]
	v_mul_f32_e32 v2, 0xbfb8aa3b, v10
	v_mul_f32_e32 v3, 0xbfb8aa3b, v11
	v_exp_f32_e32 v18, v18
	v_exp_f32_e32 v19, v19
	v_exp_f32_e32 v2, v2
	v_exp_f32_e32 v3, v3
	v_add_f32_e32 v18, 1.0, v18
	v_add_f32_e32 v19, 1.0, v19
	v_add_f32_e32 v2, 1.0, v2
	v_add_f32_e32 v3, 1.0, v3
	v_rcp_f32_e32 v18, v18
	v_rcp_f32_e32 v19, v19
	v_rcp_f32_e32 v2, v2
	v_rcp_f32_e32 v3, v3
	v_pk_fma_f32 v[112:113], v[18:19], v[58:59], v[112:113]
	v_mul_f32_e32 v18, 0xbfb8aa3b, v28
	v_mul_f32_e32 v19, 0xbfb8aa3b, v29
	v_pk_fma_f32 v[96:97], v[2:3], v[42:43], v[96:97]
	v_mul_f32_e32 v2, 0xbfb8aa3b, v12
	v_mul_f32_e32 v3, 0xbfb8aa3b, v13
	v_exp_f32_e32 v18, v18
	v_exp_f32_e32 v19, v19
	v_exp_f32_e32 v2, v2
	v_exp_f32_e32 v3, v3
	v_add_f32_e32 v18, 1.0, v18
	v_add_f32_e32 v19, 1.0, v19
	v_add_f32_e32 v2, 1.0, v2
	v_add_f32_e32 v3, 1.0, v3
	v_rcp_f32_e32 v18, v18
	v_rcp_f32_e32 v19, v19
	v_rcp_f32_e32 v2, v2
	v_rcp_f32_e32 v3, v3
	v_pk_fma_f32 v[110:111], v[18:19], v[60:61], v[110:111]
	v_mul_f32_e32 v18, 0xbfb8aa3b, v30
	v_mul_f32_e32 v19, 0xbfb8aa3b, v31
	v_pk_fma_f32 v[94:95], v[2:3], v[44:45], v[94:95]
	v_mul_f32_e32 v2, 0xbfb8aa3b, v14
	v_mul_f32_e32 v3, 0xbfb8aa3b, v15
	v_exp_f32_e32 v18, v18
	v_exp_f32_e32 v19, v19
	v_exp_f32_e32 v2, v2
	v_exp_f32_e32 v3, v3
	v_add_f32_e32 v18, 1.0, v18
	v_add_f32_e32 v19, 1.0, v19
	v_add_f32_e32 v2, 1.0, v2
	v_add_f32_e32 v3, 1.0, v3
	v_rcp_f32_e32 v18, v18
	v_rcp_f32_e32 v19, v19
	v_rcp_f32_e32 v2, v2
	v_rcp_f32_e32 v3, v3
	v_pk_fma_f32 v[108:109], v[18:19], v[62:63], v[108:109]
	v_mul_f32_e32 v18, 0xbfb8aa3b, v32
	v_mul_f32_e32 v19, 0xbfb8aa3b, v33
	v_pk_fma_f32 v[92:93], v[2:3], v[46:47], v[92:93]
	v_mul_f32_e32 v2, 0xbfb8aa3b, v16
	v_mul_f32_e32 v3, 0xbfb8aa3b, v17
	v_exp_f32_e32 v18, v18
	v_exp_f32_e32 v19, v19
	v_exp_f32_e32 v2, v2
	v_exp_f32_e32 v3, v3
	v_add_f32_e32 v18, 1.0, v18
	v_add_f32_e32 v19, 1.0, v19
	v_add_f32_e32 v2, 1.0, v2
	v_add_f32_e32 v3, 1.0, v3
	v_rcp_f32_e32 v18, v18
	v_rcp_f32_e32 v19, v19
	v_rcp_f32_e32 v2, v2
	v_rcp_f32_e32 v3, v3
	v_pk_fma_f32 v[106:107], v[18:19], v[64:65], v[106:107]
	v_pk_fma_f32 v[90:91], v[2:3], v[48:49], v[90:91]
	s_cbranch_scc0 .LBB0_1722
; #define MFMA32(a, b, c) __builtin_amdgcn_mfma_f32_32x32x16_bf16((a), (b), (c), 0, 0, 0)
; #define GEMM_LOADG(kk) { const int ka_ = amode ? (((kk) >> 6) * 96) : (kk); \
;     _Pragma("unroll") for (int i = 0; i < 4; ++i) ra[i] = *(const u32x4*)(A + (size_t)(lr + 32 * i) * lda + ka_ + lk); \
;     _Pragma("unroll") for (int i = 0; i < 2 * NT; ++i) rb[i] = *(const u32x4*)(Bt + (size_t)(lr + 32 * i) * ldb + (kk) + lk); }
; #define GEMM_STORES(buf) { u16* As_ = S + (buf) * TILE; u16* Bs_ = As_ + 128 * LS; \
;     _Pragma("unroll") for (int i = 0; i < 4; ++i) *(u32x4*)(As_ + (lr + 32 * i) * LS + lk) = ra[i]; \
;     _Pragma("unroll") for (int i = 0; i < 2 * NT; ++i) *(u32x4*)(Bs_ + (lr + 32 * i) * LS + lk) = rb[i]; }
; template <int NT>
; DI void gemm_main_np(f32x16 (&acc)[2][NT], const u16* __restrict__ A, int lda, int amode, const u16* __restrict__ Bt,
;                   int ldb, int K, char* smem) {
;     ...
;   GEMM_LOADG(0)
;   __syncthreads();
;   GEMM_STORES(0)
;   if (K > 64) GEMM_LOADG(64)
;   __syncthreads();
;   for (int k0 = 0; k0 < K; k0 += 64) {
;     const int cur = (k0 >> 6) & 1;
;     if (k0 + 64 < K) {
;       GEMM_STORES(cur ^ 1)
;       if (k0 + 128 < K) GEMM_LOADG(k0 + 128)
;     }
;     const u16* As = S + cur * TILE;
;     const u16* Bs = As + 128 * LS;
; #pragma unroll
;     for (int s = 0; s < 4; ++s) {
;       bf16x8 a[2], b[NT];
; #pragma unroll
;       for (int i = 0; i < 2; ++i) a[i] = *(const bf16x8*)(As + (wm * 64 + i * 32 + l31) * LS + s * 16 + hh * 8);
; #pragma unroll
;       for (int j = 0; j < NT; ++j) b[j] = *(const bf16x8*)(Bs + (wn * 32 * NT + j * 32 + l31) * LS + s * 16 + hh * 8);
; #pragma unroll
;       for (int i = 0; i < 2; ++i)
; #pragma unroll
;         for (int j = 0; j < NT; ++j) acc[i][j] = MFMA32(a[i], b[j], acc[i][j]);
;     }
;     __syncthreads();
.LBB0_1716:
	v_mov_b32_e32 v48, v0
	s_mov_b64 s[2:3], 0x10000
	v_ashrrev_i32_e32 v34, 3, v48
	v_lshlrev_b32_e32 v2, 4, v48
	v_and_b32_e32 v198, 0x70, v2
	v_ashrrev_i32_e32 v35, 31, v34
	v_lshl_add_u64 v[2:3], s[8:9], 0, v[198:199]
	v_lshlrev_b64 v[18:19], 11, v[34:35]
	v_lshl_add_u64 v[36:37], v[2:3], 0, v[18:19]
	v_lshl_add_u64 v[38:39], v[36:37], 0, s[2:3]
	s_mov_b32 s2, 0x10000
	v_add_co_u32_e32 v6, vcc, s2, v36
	s_mov_b64 s[2:3], 0x20000
	s_nop 0
	v_addc_co_u32_e32 v7, vcc, 0, v37, vcc
	v_lshl_add_u64 v[40:41], v[36:37], 0, s[2:3]
	s_mov_b32 s2, 0x20000
	v_add_co_u32_e32 v10, vcc, s2, v36
	s_mov_b64 s[2:3], 0x30000
	s_nop 0
	v_addc_co_u32_e32 v11, vcc, 0, v37, vcc
	v_lshl_add_u64 v[42:43], v[36:37], 0, s[2:3]
	s_mov_b32 s2, 0x30000
	v_add_co_u32_e32 v14, vcc, s2, v36
	v_and_b32_e32 v20, 7, v48
	s_add_u32 s2, s6, s26
	v_lshl_or_b32 v18, v20, 4, v18
	s_addc_u32 s3, s7, s27
	v_addc_co_u32_e32 v15, vcc, 0, v37, vcc
	v_lshl_add_u64 v[18:19], s[2:3], 0, v[18:19]
	s_mov_b32 s2, 0xd7d0000
	v_add_co_u32_e32 v44, vcc, s2, v18
	s_mov_b32 s2, 0xd7e0000
	s_nop 0
	v_addc_co_u32_e32 v45, vcc, 0, v19, vcc
	v_add_co_u32_e32 v46, vcc, s2, v18
	global_load_dwordx4 v[2:5], v[36:37], off
	s_nop 0
	global_load_dwordx4 v[6:9], v[6:7], off
	s_nop 0
	global_load_dwordx4 v[10:13], v[10:11], off
	s_nop 0
	global_load_dwordx4 v[14:17], v[14:15], off
	v_addc_co_u32_e32 v47, vcc, 0, v19, vcc
	global_load_dwordx4 v[18:21], v[44:45], off
	global_load_dwordx4 v[22:25], v[46:47], off
	s_waitcnt vmcnt(63)
	s_barrier
	global_load_dwordx4 v[26:29], v[36:37], off offset:128
	global_load_dwordx4 v[30:33], v[38:39], off offset:128
	global_load_dwordx4 v[50:53], v[40:41], off offset:128
	global_load_dwordx4 v[54:57], v[42:43], off offset:128
	global_load_dwordx4 v[58:61], v[44:45], off offset:128
	global_load_dwordx4 v[62:65], v[46:47], off offset:128
	v_and_b32_e32 v67, 31, v48
	v_lshrrev_b32_e32 v68, 1, v48
	v_and_or_b32 v35, v68, s31, v67
	v_and_b32_e32 v66, 16, v68
	v_mad_u64_u32 v[48:49], s[2:3], v34, s60, v[198:199]
	v_mad_u64_u32 v[34:35], s[2:3], v35, s60, v[66:67]
	s_cmp_lt_i32 s29, 1
	s_waitcnt vmcnt(11)
	ds_write_b128 v48, v[2:5]
	s_waitcnt vmcnt(10)
	ds_write_b128 v48, v[6:9] offset:4608
	s_waitcnt vmcnt(9)
	ds_write_b128 v48, v[10:13] offset:9216
	s_waitcnt vmcnt(8)
	ds_write_b128 v48, v[14:17] offset:13824
	s_waitcnt vmcnt(7)
	ds_write_b128 v48, v[18:21] offset:18432
	s_waitcnt vmcnt(6)
	ds_write_b128 v48, v[22:25] offset:23040
	s_waitcnt lgkmcnt(0)
	s_barrier
	s_waitcnt vmcnt(5)
	ds_write_b128 v48, v[26:29] offset:27648
	s_waitcnt vmcnt(4)
	ds_write_b128 v48, v[30:33] offset:32256
	s_waitcnt vmcnt(3)
	ds_write_b128 v48, v[50:53] offset:36864
	s_waitcnt vmcnt(2)
	ds_write_b128 v48, v[54:57] offset:41472
	s_waitcnt vmcnt(1)
	ds_write_b128 v48, v[58:61] offset:46080
	s_waitcnt vmcnt(0)
	ds_write_b128 v48, v[62:65] offset:50688
	v_and_or_b32 v6, v68, 32, v67
	v_mad_u32_u24 v35, v6, s60, v66
	ds_read_b128 v[230:233], v34
	ds_read_b128 v[166:169], v35 offset:18432
	ds_read_b128 v[170:173], v34 offset:32
	ds_read_b128 v[174:177], v35 offset:18464
	ds_read_b128 v[236:239], v34 offset:4608
	ds_read_b128 v[178:181], v34 offset:4640
	ds_read_b128 v[204:207], v34 offset:64
	ds_read_b128 v[244:247], v35 offset:18496
	ds_read_b128 v[248:251], v34 offset:96
	ds_read_b128 v[200:203], v35 offset:18528
	ds_read_b128 v[224:227], v34 offset:4672
	ds_read_b128 v[208:211], v34 offset:4704
	s_waitcnt lgkmcnt(11)
	s_waitcnt lgkmcnt(10)
	v_mfma_f32_32x32x16_bf16 v[18:33], v[230:233], v[166:169], 0
	s_waitcnt lgkmcnt(7)
	v_mfma_f32_32x32x16_bf16 v[2:17], v[236:239], v[166:169], 0
	v_mfma_f32_32x32x16_bf16 v[18:33], v[170:173], v[174:177], v[18:33]
	s_waitcnt lgkmcnt(6)
	v_mfma_f32_32x32x16_bf16 v[2:17], v[178:181], v[174:177], v[2:17]
	s_waitcnt lgkmcnt(5)
	s_waitcnt lgkmcnt(4)
	v_mfma_f32_32x32x16_bf16 v[18:33], v[204:207], v[244:247], v[18:33]
	s_waitcnt lgkmcnt(1)
	v_mfma_f32_32x32x16_bf16 v[2:17], v[224:227], v[244:247], v[2:17]
	global_load_dwordx4 v[50:53], v[36:37], off offset:256
	global_load_dwordx4 v[54:57], v[38:39], off offset:256
	global_load_dwordx4 v[70:73], v[40:41], off offset:256
	global_load_dwordx4 v[74:77], v[42:43], off offset:256
	v_mfma_f32_32x32x16_bf16 v[18:33], v[248:251], v[200:203], v[18:33]
	global_load_dwordx4 v[58:61], v[44:45], off offset:256
	global_load_dwordx4 v[78:81], v[46:47], off offset:256
	s_waitcnt lgkmcnt(0)
	s_barrier
	s_waitcnt vmcnt(5)
	ds_write_b128 v48, v[50:53]
	s_waitcnt vmcnt(4)
	ds_write_b128 v48, v[54:57] offset:4608
	s_waitcnt vmcnt(3)
	ds_write_b128 v48, v[70:73] offset:9216
	s_waitcnt vmcnt(2)
	ds_write_b128 v48, v[74:77] offset:13824
	s_waitcnt vmcnt(1)
	ds_write_b128 v48, v[58:61] offset:18432
	s_waitcnt vmcnt(0)
	ds_write_b128 v48, v[78:81] offset:23040
	ds_read_b128 v[182:185], v34 offset:27648
	ds_read_b128 v[186:189], v35 offset:46080
	ds_read_b128 v[194:197], v34 offset:27680
	ds_read_b128 v[190:193], v35 offset:46112
	ds_read_b128 v[230:233], v34 offset:32256
	ds_read_b128 v[236:239], v34 offset:32288
	ds_read_b128 v[166:169], v34 offset:27712
	ds_read_b128 v[170:173], v35 offset:46144
	ds_read_b128 v[178:181], v34 offset:27744
	ds_read_b128 v[174:177], v35 offset:46176
	ds_read_b128 v[204:207], v34 offset:32320
	ds_read_b128 v[224:227], v34 offset:32352
	global_load_dwordx4 v[142:145], v[36:37], off offset:384
	global_load_dwordx4 v[146:149], v[38:39], off offset:384
	global_load_dwordx4 v[150:153], v[40:41], off offset:384
	global_load_dwordx4 v[154:157], v[42:43], off offset:384
	global_load_dwordx4 v[158:161], v[44:45], off offset:384
	global_load_dwordx4 v[162:165], v[46:47], off offset:384
	v_mfma_f32_32x32x16_bf16 v[2:17], v[208:211], v[200:203], v[2:17]
	s_waitcnt lgkmcnt(11)
	s_waitcnt lgkmcnt(10)
	v_mfma_f32_32x32x16_bf16 v[18:33], v[182:185], v[186:189], v[18:33]
	s_waitcnt lgkmcnt(7)
	v_mfma_f32_32x32x16_bf16 v[2:17], v[230:233], v[186:189], v[2:17]
	v_mfma_f32_32x32x16_bf16 v[18:33], v[194:197], v[190:193], v[18:33]
	s_waitcnt lgkmcnt(6)
	v_mfma_f32_32x32x16_bf16 v[2:17], v[236:239], v[190:193], v[2:17]
	s_waitcnt lgkmcnt(5)
	s_waitcnt lgkmcnt(4)
	v_mfma_f32_32x32x16_bf16 v[18:33], v[166:169], v[170:173], v[18:33]
	s_waitcnt lgkmcnt(1)
	v_mfma_f32_32x32x16_bf16 v[2:17], v[204:207], v[170:173], v[2:17]
	s_waitcnt lgkmcnt(0)
	s_barrier
; #define MFMA32(a, b, c) __builtin_amdgcn_mfma_f32_32x32x16_bf16((a), (b), (c), 0, 0, 0)
; #define GEMM_LOADG(kk) { const int ka_ = amode ? (((kk) >> 6) * 96) : (kk); \
;     _Pragma("unroll") for (int i = 0; i < 4; ++i) ra[i] = *(const u32x4*)(A + (size_t)(lr + 32 * i) * lda + ka_ + lk); \
;     _Pragma("unroll") for (int i = 0; i < 2 * NT; ++i) rb[i] = *(const u32x4*)(Bt + (size_t)(lr + 32 * i) * ldb + (kk) + lk); }
; #define GEMM_STORES(buf) { u16* As_ = S + (buf) * TILE; u16* Bs_ = As_ + 128 * LS; \
;     _Pragma("unroll") for (int i = 0; i < 4; ++i) *(u32x4*)(As_ + (lr + 32 * i) * LS + lk) = ra[i]; \
;     _Pragma("unroll") for (int i = 0; i < 2 * NT; ++i) *(u32x4*)(Bs_ + (lr + 32 * i) * LS + lk) = rb[i]; }
; template <int NT>
; DI void gemm_main_np(f32x16 (&acc)[2][NT], const u16* __restrict__ A, int lda, int amode, const u16* __restrict__ Bt,
;                   int ldb, int K, char* smem) {
;     ...
;   for (int k0 = 0; k0 < K; k0 += 64) {
;     const int cur = (k0 >> 6) & 1;
;     if (k0 + 64 < K) {
;       GEMM_STORES(cur ^ 1)
;       if (k0 + 128 < K) GEMM_LOADG(k0 + 128)
;     }
;     const u16* As = S + cur * TILE;
;     const u16* Bs = As + 128 * LS;
; #pragma unroll
;     for (int s = 0; s < 4; ++s) {
;       bf16x8 a[2], b[NT];
; #pragma unroll
;       for (int i = 0; i < 2; ++i) a[i] = *(const bf16x8*)(As + (wm * 64 + i * 32 + l31) * LS + s * 16 + hh * 8);
; #pragma unroll
;       for (int j = 0; j < NT; ++j) b[j] = *(const bf16x8*)(Bs + (wn * 32 * NT + j * 32 + l31) * LS + s * 16 + hh * 8);
; #pragma unroll
;       for (int i = 0; i < 2; ++i)
; #pragma unroll
;         for (int j = 0; j < NT; ++j) acc[i][j] = MFMA32(a[i], b[j], acc[i][j]);
;     }
;     __syncthreads();
	s_waitcnt vmcnt(5)
	ds_write_b128 v48, v[142:145] offset:27648
	s_waitcnt vmcnt(4)
	ds_write_b128 v48, v[146:149] offset:32256
	s_waitcnt vmcnt(3)
	ds_write_b128 v48, v[150:153] offset:36864
	s_waitcnt vmcnt(2)
	ds_write_b128 v48, v[154:157] offset:41472
	s_waitcnt vmcnt(1)
	ds_write_b128 v48, v[158:161] offset:46080
	s_waitcnt vmcnt(0)
	ds_write_b128 v48, v[162:165] offset:50688
	ds_read_b128 v[244:247], v34
	ds_read_b128 v[248:251], v35 offset:18432
	ds_read_b128 v[208:211], v34 offset:32
	ds_read_b128 v[200:203], v35 offset:18464
	ds_read_b128 v[182:185], v34 offset:4608
	ds_read_b128 v[230:233], v34 offset:4640
	ds_read_b128 v[186:189], v34 offset:64
	ds_read_b128 v[194:197], v35 offset:18496
	ds_read_b128 v[236:239], v34 offset:96
	ds_read_b128 v[190:193], v35 offset:18528
	ds_read_b128 v[166:169], v34 offset:4672
	ds_read_b128 v[204:207], v34 offset:4704
	global_load_dwordx4 v[142:145], v[36:37], off offset:512
	global_load_dwordx4 v[146:149], v[38:39], off offset:512
	global_load_dwordx4 v[150:153], v[40:41], off offset:512
	global_load_dwordx4 v[154:157], v[42:43], off offset:512
	global_load_dwordx4 v[158:161], v[44:45], off offset:512
	global_load_dwordx4 v[162:165], v[46:47], off offset:512
	v_mfma_f32_32x32x16_bf16 v[18:33], v[178:181], v[174:177], v[18:33]
	v_mfma_f32_32x32x16_bf16 v[2:17], v[224:227], v[174:177], v[2:17]
	s_waitcnt lgkmcnt(11)
	s_waitcnt lgkmcnt(10)
	v_mfma_f32_32x32x16_bf16 v[18:33], v[244:247], v[248:251], v[18:33]
	s_waitcnt lgkmcnt(7)
	v_mfma_f32_32x32x16_bf16 v[2:17], v[182:185], v[248:251], v[2:17]
	v_mfma_f32_32x32x16_bf16 v[18:33], v[208:211], v[200:203], v[18:33]
	s_waitcnt lgkmcnt(6)
	v_mfma_f32_32x32x16_bf16 v[2:17], v[230:233], v[200:203], v[2:17]
	s_waitcnt lgkmcnt(5)
	s_waitcnt lgkmcnt(4)
	v_mfma_f32_32x32x16_bf16 v[18:33], v[186:189], v[194:197], v[18:33]
	s_waitcnt lgkmcnt(1)
	v_mfma_f32_32x32x16_bf16 v[2:17], v[166:169], v[194:197], v[2:17]
	v_mfma_f32_32x32x16_bf16 v[18:33], v[236:239], v[190:193], v[18:33]
	s_waitcnt lgkmcnt(0)
	s_barrier
	s_waitcnt vmcnt(5)
	ds_write_b128 v48, v[142:145]
	s_waitcnt vmcnt(4)
	ds_write_b128 v48, v[146:149] offset:4608
	s_waitcnt vmcnt(3)
	ds_write_b128 v48, v[150:153] offset:9216
	s_waitcnt vmcnt(2)
	ds_write_b128 v48, v[154:157] offset:13824
	s_waitcnt vmcnt(1)
	ds_write_b128 v48, v[158:161] offset:18432
	s_waitcnt vmcnt(0)
	ds_write_b128 v48, v[162:165] offset:23040
	ds_read_b128 v[170:173], v34 offset:27648
	ds_read_b128 v[178:181], v35 offset:46080
	ds_read_b128 v[224:227], v34 offset:27680
	ds_read_b128 v[174:177], v35 offset:46112
	ds_read_b128 v[244:247], v34 offset:32256
	ds_read_b128 v[182:185], v34 offset:32288
	ds_read_b128 v[248:251], v34 offset:27712
	ds_read_b128 v[208:211], v35 offset:46144
	ds_read_b128 v[230:233], v34 offset:27744
	ds_read_b128 v[200:203], v35 offset:46176
	ds_read_b128 v[186:189], v34 offset:32320
	ds_read_b128 v[166:169], v34 offset:32352
	global_load_dwordx4 v[142:145], v[36:37], off offset:640
	global_load_dwordx4 v[146:149], v[38:39], off offset:640
	global_load_dwordx4 v[150:153], v[40:41], off offset:640
	global_load_dwordx4 v[154:157], v[42:43], off offset:640
	global_load_dwordx4 v[158:161], v[44:45], off offset:640
	global_load_dwordx4 v[162:165], v[46:47], off offset:640
	v_mfma_f32_32x32x16_bf16 v[2:17], v[204:207], v[190:193], v[2:17]
	s_waitcnt lgkmcnt(11)
	s_waitcnt lgkmcnt(10)
	v_mfma_f32_32x32x16_bf16 v[18:33], v[170:173], v[178:181], v[18:33]
	s_waitcnt lgkmcnt(7)
	v_mfma_f32_32x32x16_bf16 v[2:17], v[244:247], v[178:181], v[2:17]
	v_mfma_f32_32x32x16_bf16 v[18:33], v[224:227], v[174:177], v[18:33]
	s_waitcnt lgkmcnt(6)
	v_mfma_f32_32x32x16_bf16 v[2:17], v[182:185], v[174:177], v[2:17]
	s_waitcnt lgkmcnt(5)
	s_waitcnt lgkmcnt(4)
	v_mfma_f32_32x32x16_bf16 v[18:33], v[248:251], v[208:211], v[18:33]
	s_waitcnt lgkmcnt(1)
	v_mfma_f32_32x32x16_bf16 v[2:17], v[186:189], v[208:211], v[2:17]
	s_waitcnt lgkmcnt(0)
	s_barrier
	s_waitcnt vmcnt(5)
	ds_write_b128 v48, v[142:145] offset:27648
	s_waitcnt vmcnt(4)
	ds_write_b128 v48, v[146:149] offset:32256
	s_waitcnt vmcnt(3)
	ds_write_b128 v48, v[150:153] offset:36864
	s_waitcnt vmcnt(2)
	ds_write_b128 v48, v[154:157] offset:41472
	s_waitcnt vmcnt(1)
	ds_write_b128 v48, v[158:161] offset:46080
	s_waitcnt vmcnt(0)
	ds_write_b128 v48, v[162:165] offset:50688
	ds_read_b128 v[194:197], v34
	ds_read_b128 v[236:239], v35 offset:18432
	ds_read_b128 v[204:207], v34 offset:32
	ds_read_b128 v[190:193], v35 offset:18464
	ds_read_b128 v[170:173], v34 offset:4608
	ds_read_b128 v[244:247], v34 offset:4640
	ds_read_b128 v[178:181], v34 offset:64
	ds_read_b128 v[224:227], v35 offset:18496
	ds_read_b128 v[182:185], v34 offset:96
	ds_read_b128 v[174:177], v35 offset:18528
	ds_read_b128 v[248:251], v34 offset:4672
	ds_read_b128 v[186:189], v34 offset:4704
	global_load_dwordx4 v[142:145], v[36:37], off offset:768
	global_load_dwordx4 v[146:149], v[38:39], off offset:768
	global_load_dwordx4 v[150:153], v[40:41], off offset:768
	global_load_dwordx4 v[154:157], v[42:43], off offset:768
	global_load_dwordx4 v[158:161], v[44:45], off offset:768
	global_load_dwordx4 v[162:165], v[46:47], off offset:768
	v_mfma_f32_32x32x16_bf16 v[18:33], v[230:233], v[200:203], v[18:33]
	v_mfma_f32_32x32x16_bf16 v[2:17], v[166:169], v[200:203], v[2:17]
	s_waitcnt lgkmcnt(11)
	s_waitcnt lgkmcnt(10)
	v_mfma_f32_32x32x16_bf16 v[18:33], v[194:197], v[236:239], v[18:33]
	s_waitcnt lgkmcnt(7)
	v_mfma_f32_32x32x16_bf16 v[2:17], v[170:173], v[236:239], v[2:17]
	v_mfma_f32_32x32x16_bf16 v[18:33], v[204:207], v[190:193], v[18:33]
	s_waitcnt lgkmcnt(6)
	v_mfma_f32_32x32x16_bf16 v[2:17], v[244:247], v[190:193], v[2:17]
	s_waitcnt lgkmcnt(5)
	s_waitcnt lgkmcnt(4)
	v_mfma_f32_32x32x16_bf16 v[18:33], v[178:181], v[224:227], v[18:33]
	s_waitcnt lgkmcnt(1)
	v_mfma_f32_32x32x16_bf16 v[2:17], v[248:251], v[224:227], v[2:17]
	v_mfma_f32_32x32x16_bf16 v[18:33], v[182:185], v[174:177], v[18:33]
	s_waitcnt lgkmcnt(0)
	s_barrier
; #define MFMA32(a, b, c) __builtin_amdgcn_mfma_f32_32x32x16_bf16((a), (b), (c), 0, 0, 0)
; #define GEMM_LOADG(kk) { const int ka_ = amode ? (((kk) >> 6) * 96) : (kk); \
;     _Pragma("unroll") for (int i = 0; i < 4; ++i) ra[i] = *(const u32x4*)(A + (size_t)(lr + 32 * i) * lda + ka_ + lk); \
;     _Pragma("unroll") for (int i = 0; i < 2 * NT; ++i) rb[i] = *(const u32x4*)(Bt + (size_t)(lr + 32 * i) * ldb + (kk) + lk); }
; #define GEMM_STORES(buf) { u16* As_ = S + (buf) * TILE; u16* Bs_ = As_ + 128 * LS; \
;     _Pragma("unroll") for (int i = 0; i < 4; ++i) *(u32x4*)(As_ + (lr + 32 * i) * LS + lk) = ra[i]; \
;     _Pragma("unroll") for (int i = 0; i < 2 * NT; ++i) *(u32x4*)(Bs_ + (lr + 32 * i) * LS + lk) = rb[i]; }
; template <int NT>
; DI void gemm_main_np(f32x16 (&acc)[2][NT], const u16* __restrict__ A, int lda, int amode, const u16* __restrict__ Bt,
;                   int ldb, int K, char* smem) {
;     ...
;   for (int k0 = 0; k0 < K; k0 += 64) {
;     const int cur = (k0 >> 6) & 1;
;     if (k0 + 64 < K) {
;       GEMM_STORES(cur ^ 1)
;       if (k0 + 128 < K) GEMM_LOADG(k0 + 128)
;     }
;     const u16* As = S + cur * TILE;
;     const u16* Bs = As + 128 * LS;
; #pragma unroll
;     for (int s = 0; s < 4; ++s) {
;       bf16x8 a[2], b[NT];
; #pragma unroll
;       for (int i = 0; i < 2; ++i) a[i] = *(const bf16x8*)(As + (wm * 64 + i * 32 + l31) * LS + s * 16 + hh * 8);
; #pragma unroll
;       for (int j = 0; j < NT; ++j) b[j] = *(const bf16x8*)(Bs + (wn * 32 * NT + j * 32 + l31) * LS + s * 16 + hh * 8);
; #pragma unroll
;       for (int i = 0; i < 2; ++i)
; #pragma unroll
;         for (int j = 0; j < NT; ++j) acc[i][j] = MFMA32(a[i], b[j], acc[i][j]);
;     }
;     __syncthreads();
	s_waitcnt vmcnt(5)
	ds_write_b128 v48, v[142:145]
	s_waitcnt vmcnt(4)
	ds_write_b128 v48, v[146:149] offset:4608
	s_waitcnt vmcnt(3)
	ds_write_b128 v48, v[150:153] offset:9216
	s_waitcnt vmcnt(2)
	ds_write_b128 v48, v[154:157] offset:13824
	s_waitcnt vmcnt(1)
	ds_write_b128 v48, v[158:161] offset:18432
	s_waitcnt vmcnt(0)
	ds_write_b128 v48, v[162:165] offset:23040
	ds_read_b128 v[208:211], v34 offset:27648
	ds_read_b128 v[230:233], v35 offset:46080
	ds_read_b128 v[166:169], v34 offset:27680
	ds_read_b128 v[200:203], v35 offset:46112
	ds_read_b128 v[194:197], v34 offset:32256
	ds_read_b128 v[170:173], v34 offset:32288
	ds_read_b128 v[236:239], v34 offset:27712
	ds_read_b128 v[204:207], v35 offset:46144
	ds_read_b128 v[244:247], v34 offset:27744
	ds_read_b128 v[190:193], v35 offset:46176
	ds_read_b128 v[178:181], v34 offset:32320
	ds_read_b128 v[248:251], v34 offset:32352
	global_load_dwordx4 v[142:145], v[36:37], off offset:896
	global_load_dwordx4 v[146:149], v[38:39], off offset:896
	global_load_dwordx4 v[150:153], v[40:41], off offset:896
	global_load_dwordx4 v[154:157], v[42:43], off offset:896
	global_load_dwordx4 v[158:161], v[44:45], off offset:896
	global_load_dwordx4 v[162:165], v[46:47], off offset:896
	v_mfma_f32_32x32x16_bf16 v[2:17], v[186:189], v[174:177], v[2:17]
	s_waitcnt lgkmcnt(11)
	s_waitcnt lgkmcnt(10)
	v_mfma_f32_32x32x16_bf16 v[18:33], v[208:211], v[230:233], v[18:33]
	s_waitcnt lgkmcnt(7)
	v_mfma_f32_32x32x16_bf16 v[2:17], v[194:197], v[230:233], v[2:17]
	v_mfma_f32_32x32x16_bf16 v[18:33], v[166:169], v[200:203], v[18:33]
	s_waitcnt lgkmcnt(6)
	v_mfma_f32_32x32x16_bf16 v[2:17], v[170:173], v[200:203], v[2:17]
	s_waitcnt lgkmcnt(5)
	s_waitcnt lgkmcnt(4)
	v_mfma_f32_32x32x16_bf16 v[18:33], v[236:239], v[204:207], v[18:33]
	s_waitcnt lgkmcnt(1)
	v_mfma_f32_32x32x16_bf16 v[2:17], v[178:181], v[204:207], v[2:17]
	v_mfma_f32_32x32x16_bf16 v[18:33], v[244:247], v[190:193], v[18:33]
	s_waitcnt lgkmcnt(0)
	s_barrier
	s_waitcnt vmcnt(5)
	ds_write_b128 v48, v[142:145] offset:27648
	s_waitcnt vmcnt(4)
	ds_write_b128 v48, v[146:149] offset:32256
	s_waitcnt vmcnt(3)
	ds_write_b128 v48, v[150:153] offset:36864
	s_waitcnt vmcnt(2)
	ds_write_b128 v48, v[154:157] offset:41472
	s_waitcnt vmcnt(1)
	ds_write_b128 v48, v[158:161] offset:46080
	s_waitcnt vmcnt(0)
	ds_write_b128 v48, v[162:165] offset:50688
	ds_read_b128 v[224:227], v34
	ds_read_b128 v[182:185], v35 offset:18432
	ds_read_b128 v[186:189], v34 offset:32
	ds_read_b128 v[174:177], v35 offset:18464
	ds_read_b128 v[208:211], v34 offset:4608
	ds_read_b128 v[194:197], v34 offset:4640
	ds_read_b128 v[230:233], v34 offset:64
	ds_read_b128 v[166:169], v35 offset:18496
	ds_read_b128 v[170:173], v34 offset:96
	ds_read_b128 v[200:203], v35 offset:18528
	ds_read_b128 v[236:239], v34 offset:4672
	ds_read_b128 v[178:181], v34 offset:4704
	global_load_dwordx4 v[142:145], v[36:37], off offset:1024
	global_load_dwordx4 v[146:149], v[38:39], off offset:1024
	global_load_dwordx4 v[150:153], v[40:41], off offset:1024
	global_load_dwordx4 v[154:157], v[42:43], off offset:1024
	global_load_dwordx4 v[158:161], v[44:45], off offset:1024
	global_load_dwordx4 v[162:165], v[46:47], off offset:1024
	v_mfma_f32_32x32x16_bf16 v[2:17], v[248:251], v[190:193], v[2:17]
	s_waitcnt lgkmcnt(11)
	s_waitcnt lgkmcnt(10)
	v_mfma_f32_32x32x16_bf16 v[18:33], v[224:227], v[182:185], v[18:33]
	s_waitcnt lgkmcnt(7)
	v_mfma_f32_32x32x16_bf16 v[2:17], v[208:211], v[182:185], v[2:17]
	v_mfma_f32_32x32x16_bf16 v[18:33], v[186:189], v[174:177], v[18:33]
	s_waitcnt lgkmcnt(6)
	v_mfma_f32_32x32x16_bf16 v[2:17], v[194:197], v[174:177], v[2:17]
	s_waitcnt lgkmcnt(5)
	s_waitcnt lgkmcnt(4)
	v_mfma_f32_32x32x16_bf16 v[18:33], v[230:233], v[166:169], v[18:33]
	s_waitcnt lgkmcnt(1)
	v_mfma_f32_32x32x16_bf16 v[2:17], v[236:239], v[166:169], v[2:17]
	v_mfma_f32_32x32x16_bf16 v[18:33], v[170:173], v[200:203], v[18:33]
	s_waitcnt lgkmcnt(0)
	s_barrier
	s_waitcnt vmcnt(5)
	ds_write_b128 v48, v[142:145]
	s_waitcnt vmcnt(4)
	ds_write_b128 v48, v[146:149] offset:4608
	s_waitcnt vmcnt(3)
	ds_write_b128 v48, v[150:153] offset:9216
	s_waitcnt vmcnt(2)
	ds_write_b128 v48, v[154:157] offset:13824
	s_waitcnt vmcnt(1)
	ds_write_b128 v48, v[158:161] offset:18432
	s_waitcnt vmcnt(0)
	ds_write_b128 v48, v[162:165] offset:23040
	ds_read_b128 v[204:207], v34 offset:27648
	ds_read_b128 v[244:247], v35 offset:46080
	ds_read_b128 v[248:251], v34 offset:27680
	ds_read_b128 v[190:193], v35 offset:46112
	ds_read_b128 v[224:227], v34 offset:32256
	ds_read_b128 v[208:211], v34 offset:32288
	ds_read_b128 v[182:185], v34 offset:27712
	ds_read_b128 v[186:189], v35 offset:46144
	ds_read_b128 v[194:197], v34 offset:27744
	ds_read_b128 v[174:177], v35 offset:46176
	ds_read_b128 v[230:233], v34 offset:32320
	ds_read_b128 v[236:239], v34 offset:32352
	global_load_dwordx4 v[142:145], v[36:37], off offset:1152
	global_load_dwordx4 v[146:149], v[38:39], off offset:1152
	global_load_dwordx4 v[150:153], v[40:41], off offset:1152
	global_load_dwordx4 v[154:157], v[42:43], off offset:1152
	global_load_dwordx4 v[158:161], v[44:45], off offset:1152
	global_load_dwordx4 v[162:165], v[46:47], off offset:1152
	v_mfma_f32_32x32x16_bf16 v[2:17], v[178:181], v[200:203], v[2:17]
	s_waitcnt lgkmcnt(11)
	s_waitcnt lgkmcnt(10)
	v_mfma_f32_32x32x16_bf16 v[18:33], v[204:207], v[244:247], v[18:33]
	s_waitcnt lgkmcnt(7)
	v_mfma_f32_32x32x16_bf16 v[2:17], v[224:227], v[244:247], v[2:17]
	v_mfma_f32_32x32x16_bf16 v[18:33], v[248:251], v[190:193], v[18:33]
	s_waitcnt lgkmcnt(6)
	v_mfma_f32_32x32x16_bf16 v[2:17], v[208:211], v[190:193], v[2:17]
	s_waitcnt lgkmcnt(5)
	s_waitcnt lgkmcnt(4)
	v_mfma_f32_32x32x16_bf16 v[18:33], v[182:185], v[186:189], v[18:33]
	s_waitcnt lgkmcnt(1)
	v_mfma_f32_32x32x16_bf16 v[2:17], v[230:233], v[186:189], v[2:17]
	v_mfma_f32_32x32x16_bf16 v[18:33], v[194:197], v[174:177], v[18:33]
	s_waitcnt lgkmcnt(0)
	s_barrier
; #define MFMA32(a, b, c) __builtin_amdgcn_mfma_f32_32x32x16_bf16((a), (b), (c), 0, 0, 0)
; #define GEMM_LOADG(kk) { const int ka_ = amode ? (((kk) >> 6) * 96) : (kk); \
;     _Pragma("unroll") for (int i = 0; i < 4; ++i) ra[i] = *(const u32x4*)(A + (size_t)(lr + 32 * i) * lda + ka_ + lk); \
;     _Pragma("unroll") for (int i = 0; i < 2 * NT; ++i) rb[i] = *(const u32x4*)(Bt + (size_t)(lr + 32 * i) * ldb + (kk) + lk); }
; #define GEMM_STORES(buf) { u16* As_ = S + (buf) * TILE; u16* Bs_ = As_ + 128 * LS; \
;     _Pragma("unroll") for (int i = 0; i < 4; ++i) *(u32x4*)(As_ + (lr + 32 * i) * LS + lk) = ra[i]; \
;     _Pragma("unroll") for (int i = 0; i < 2 * NT; ++i) *(u32x4*)(Bs_ + (lr + 32 * i) * LS + lk) = rb[i]; }
; template <int NT>
; DI void gemm_main_np(f32x16 (&acc)[2][NT], const u16* __restrict__ A, int lda, int amode, const u16* __restrict__ Bt,
;                   int ldb, int K, char* smem) {
;     ...
;   for (int k0 = 0; k0 < K; k0 += 64) {
;     const int cur = (k0 >> 6) & 1;
;     if (k0 + 64 < K) {
;       GEMM_STORES(cur ^ 1)
;       if (k0 + 128 < K) GEMM_LOADG(k0 + 128)
;     }
;     const u16* As = S + cur * TILE;
;     const u16* Bs = As + 128 * LS;
; #pragma unroll
;     for (int s = 0; s < 4; ++s) {
;       bf16x8 a[2], b[NT];
; #pragma unroll
;       for (int i = 0; i < 2; ++i) a[i] = *(const bf16x8*)(As + (wm * 64 + i * 32 + l31) * LS + s * 16 + hh * 8);
; #pragma unroll
;       for (int j = 0; j < NT; ++j) b[j] = *(const bf16x8*)(Bs + (wn * 32 * NT + j * 32 + l31) * LS + s * 16 + hh * 8);
; #pragma unroll
;       for (int i = 0; i < 2; ++i)
; #pragma unroll
;         for (int j = 0; j < NT; ++j) acc[i][j] = MFMA32(a[i], b[j], acc[i][j]);
;     }
;     __syncthreads();
	s_waitcnt vmcnt(5)
	ds_write_b128 v48, v[142:145] offset:27648
	s_waitcnt vmcnt(4)
	ds_write_b128 v48, v[146:149] offset:32256
	s_waitcnt vmcnt(3)
	ds_write_b128 v48, v[150:153] offset:36864
	s_waitcnt vmcnt(2)
	ds_write_b128 v48, v[154:157] offset:41472
	s_waitcnt vmcnt(1)
	ds_write_b128 v48, v[158:161] offset:46080
	s_waitcnt vmcnt(0)
	ds_write_b128 v48, v[162:165] offset:50688
	ds_read_b128 v[166:169], v34
	ds_read_b128 v[170:173], v35 offset:18432
	ds_read_b128 v[178:181], v34 offset:32
	ds_read_b128 v[200:203], v35 offset:18464
	ds_read_b128 v[204:207], v34 offset:4608
	ds_read_b128 v[224:227], v34 offset:4640
	ds_read_b128 v[244:247], v34 offset:64
	ds_read_b128 v[248:251], v35 offset:18496
	ds_read_b128 v[208:211], v34 offset:96
	ds_read_b128 v[190:193], v35 offset:18528
	ds_read_b128 v[182:185], v34 offset:4672
	ds_read_b128 v[230:233], v34 offset:4704
	global_load_dwordx4 v[142:145], v[36:37], off offset:1280
	global_load_dwordx4 v[146:149], v[38:39], off offset:1280
	global_load_dwordx4 v[150:153], v[40:41], off offset:1280
	global_load_dwordx4 v[154:157], v[42:43], off offset:1280
	global_load_dwordx4 v[158:161], v[44:45], off offset:1280
	global_load_dwordx4 v[162:165], v[46:47], off offset:1280
	v_mfma_f32_32x32x16_bf16 v[2:17], v[236:239], v[174:177], v[2:17]
	s_waitcnt lgkmcnt(11)
	s_waitcnt lgkmcnt(10)
	v_mfma_f32_32x32x16_bf16 v[18:33], v[166:169], v[170:173], v[18:33]
	s_waitcnt lgkmcnt(7)
	v_mfma_f32_32x32x16_bf16 v[2:17], v[204:207], v[170:173], v[2:17]
	v_mfma_f32_32x32x16_bf16 v[18:33], v[178:181], v[200:203], v[18:33]
	s_waitcnt lgkmcnt(6)
	v_mfma_f32_32x32x16_bf16 v[2:17], v[224:227], v[200:203], v[2:17]
	s_waitcnt lgkmcnt(5)
	s_waitcnt lgkmcnt(4)
	v_mfma_f32_32x32x16_bf16 v[18:33], v[244:247], v[248:251], v[18:33]
	s_waitcnt lgkmcnt(1)
	v_mfma_f32_32x32x16_bf16 v[2:17], v[182:185], v[248:251], v[2:17]
	v_mfma_f32_32x32x16_bf16 v[18:33], v[208:211], v[190:193], v[18:33]
	s_waitcnt lgkmcnt(0)
	s_barrier
	s_waitcnt vmcnt(5)
	ds_write_b128 v48, v[142:145]
	s_waitcnt vmcnt(4)
	ds_write_b128 v48, v[146:149] offset:4608
	s_waitcnt vmcnt(3)
	ds_write_b128 v48, v[150:153] offset:9216
	s_waitcnt vmcnt(2)
	ds_write_b128 v48, v[154:157] offset:13824
	s_waitcnt vmcnt(1)
	ds_write_b128 v48, v[158:161] offset:18432
	s_waitcnt vmcnt(0)
	ds_write_b128 v48, v[162:165] offset:23040
	ds_read_b128 v[186:189], v34 offset:27648
	ds_read_b128 v[194:197], v35 offset:46080
	ds_read_b128 v[236:239], v34 offset:27680
	ds_read_b128 v[174:177], v35 offset:46112
	ds_read_b128 v[166:169], v34 offset:32256
	ds_read_b128 v[204:207], v34 offset:32288
	ds_read_b128 v[170:173], v34 offset:27712
	ds_read_b128 v[178:181], v35 offset:46144
	ds_read_b128 v[224:227], v34 offset:27744
	ds_read_b128 v[200:203], v35 offset:46176
	ds_read_b128 v[244:247], v34 offset:32320
	ds_read_b128 v[182:185], v34 offset:32352
	global_load_dwordx4 v[142:145], v[36:37], off offset:1408
	global_load_dwordx4 v[146:149], v[38:39], off offset:1408
	global_load_dwordx4 v[150:153], v[40:41], off offset:1408
	global_load_dwordx4 v[154:157], v[42:43], off offset:1408
	global_load_dwordx4 v[158:161], v[44:45], off offset:1408
	global_load_dwordx4 v[162:165], v[46:47], off offset:1408
	v_mfma_f32_32x32x16_bf16 v[2:17], v[230:233], v[190:193], v[2:17]
	s_waitcnt lgkmcnt(11)
	s_waitcnt lgkmcnt(10)
	v_mfma_f32_32x32x16_bf16 v[18:33], v[186:189], v[194:197], v[18:33]
	s_waitcnt lgkmcnt(7)
	v_mfma_f32_32x32x16_bf16 v[2:17], v[166:169], v[194:197], v[2:17]
	v_mfma_f32_32x32x16_bf16 v[18:33], v[236:239], v[174:177], v[18:33]
	s_waitcnt lgkmcnt(6)
	v_mfma_f32_32x32x16_bf16 v[2:17], v[204:207], v[174:177], v[2:17]
	s_waitcnt lgkmcnt(5)
	s_waitcnt lgkmcnt(4)
	v_mfma_f32_32x32x16_bf16 v[18:33], v[170:173], v[178:181], v[18:33]
	s_waitcnt lgkmcnt(1)
	v_mfma_f32_32x32x16_bf16 v[2:17], v[244:247], v[178:181], v[2:17]
	v_mfma_f32_32x32x16_bf16 v[18:33], v[224:227], v[200:203], v[18:33]
	s_waitcnt lgkmcnt(0)
	s_barrier
	s_waitcnt vmcnt(5)
	ds_write_b128 v48, v[142:145] offset:27648
	s_waitcnt vmcnt(4)
	ds_write_b128 v48, v[146:149] offset:32256
	s_waitcnt vmcnt(3)
	ds_write_b128 v48, v[150:153] offset:36864
	s_waitcnt vmcnt(2)
	ds_write_b128 v48, v[154:157] offset:41472
	s_waitcnt vmcnt(1)
	ds_write_b128 v48, v[158:161] offset:46080
	s_waitcnt vmcnt(0)
	ds_write_b128 v48, v[162:165] offset:50688
	ds_read_b128 v[248:251], v34
	ds_read_b128 v[208:211], v35 offset:18432
	ds_read_b128 v[230:233], v34 offset:32
	ds_read_b128 v[190:193], v35 offset:18464
	ds_read_b128 v[186:189], v34 offset:4608
	ds_read_b128 v[166:169], v34 offset:4640
	ds_read_b128 v[194:197], v34 offset:64
	ds_read_b128 v[236:239], v35 offset:18496
	ds_read_b128 v[204:207], v34 offset:96
	ds_read_b128 v[174:177], v35 offset:18528
	ds_read_b128 v[170:173], v34 offset:4672
	ds_read_b128 v[244:247], v34 offset:4704
	global_load_dwordx4 v[142:145], v[36:37], off offset:1536
	global_load_dwordx4 v[146:149], v[38:39], off offset:1536
	global_load_dwordx4 v[150:153], v[40:41], off offset:1536
	global_load_dwordx4 v[154:157], v[42:43], off offset:1536
	global_load_dwordx4 v[158:161], v[44:45], off offset:1536
	global_load_dwordx4 v[162:165], v[46:47], off offset:1536
	v_mfma_f32_32x32x16_bf16 v[2:17], v[182:185], v[200:203], v[2:17]
	s_waitcnt lgkmcnt(11)
	s_waitcnt lgkmcnt(10)
	v_mfma_f32_32x32x16_bf16 v[18:33], v[248:251], v[208:211], v[18:33]
	s_waitcnt lgkmcnt(7)
	v_mfma_f32_32x32x16_bf16 v[2:17], v[186:189], v[208:211], v[2:17]
	v_mfma_f32_32x32x16_bf16 v[18:33], v[230:233], v[190:193], v[18:33]
	s_waitcnt lgkmcnt(6)
	v_mfma_f32_32x32x16_bf16 v[2:17], v[166:169], v[190:193], v[2:17]
	s_waitcnt lgkmcnt(5)
	s_waitcnt lgkmcnt(4)
	v_mfma_f32_32x32x16_bf16 v[18:33], v[194:197], v[236:239], v[18:33]
	s_waitcnt lgkmcnt(1)
	v_mfma_f32_32x32x16_bf16 v[2:17], v[170:173], v[236:239], v[2:17]
	v_mfma_f32_32x32x16_bf16 v[18:33], v[204:207], v[174:177], v[18:33]
	s_waitcnt lgkmcnt(0)
	s_barrier
; #define MFMA32(a, b, c) __builtin_amdgcn_mfma_f32_32x32x16_bf16((a), (b), (c), 0, 0, 0)
; #define GEMM_LOADG(kk) { const int ka_ = amode ? (((kk) >> 6) * 96) : (kk); \
;     _Pragma("unroll") for (int i = 0; i < 4; ++i) ra[i] = *(const u32x4*)(A + (size_t)(lr + 32 * i) * lda + ka_ + lk); \
;     _Pragma("unroll") for (int i = 0; i < 2 * NT; ++i) rb[i] = *(const u32x4*)(Bt + (size_t)(lr + 32 * i) * ldb + (kk) + lk); }
; #define GEMM_STORES(buf) { u16* As_ = S + (buf) * TILE; u16* Bs_ = As_ + 128 * LS; \
;     _Pragma("unroll") for (int i = 0; i < 4; ++i) *(u32x4*)(As_ + (lr + 32 * i) * LS + lk) = ra[i]; \
;     _Pragma("unroll") for (int i = 0; i < 2 * NT; ++i) *(u32x4*)(Bs_ + (lr + 32 * i) * LS + lk) = rb[i]; }
; template <int NT>
; DI void gemm_main_np(f32x16 (&acc)[2][NT], const u16* __restrict__ A, int lda, int amode, const u16* __restrict__ Bt,
;                   int ldb, int K, char* smem) {
;     ...
;   for (int k0 = 0; k0 < K; k0 += 64) {
;     const int cur = (k0 >> 6) & 1;
;     if (k0 + 64 < K) {
;       GEMM_STORES(cur ^ 1)
;       if (k0 + 128 < K) GEMM_LOADG(k0 + 128)
;     }
;     const u16* As = S + cur * TILE;
;     const u16* Bs = As + 128 * LS;
; #pragma unroll
;     for (int s = 0; s < 4; ++s) {
;       bf16x8 a[2], b[NT];
; #pragma unroll
;       for (int i = 0; i < 2; ++i) a[i] = *(const bf16x8*)(As + (wm * 64 + i * 32 + l31) * LS + s * 16 + hh * 8);
; #pragma unroll
;       for (int j = 0; j < NT; ++j) b[j] = *(const bf16x8*)(Bs + (wn * 32 * NT + j * 32 + l31) * LS + s * 16 + hh * 8);
; #pragma unroll
;       for (int i = 0; i < 2; ++i)
; #pragma unroll
;         for (int j = 0; j < NT; ++j) acc[i][j] = MFMA32(a[i], b[j], acc[i][j]);
;     }
;     __syncthreads();
	s_waitcnt vmcnt(5)
	ds_write_b128 v48, v[142:145]
	s_waitcnt vmcnt(4)
	ds_write_b128 v48, v[146:149] offset:4608
	s_waitcnt vmcnt(3)
	ds_write_b128 v48, v[150:153] offset:9216
	s_waitcnt vmcnt(2)
	ds_write_b128 v48, v[154:157] offset:13824
	s_waitcnt vmcnt(1)
	ds_write_b128 v48, v[158:161] offset:18432
	s_waitcnt vmcnt(0)
	ds_write_b128 v48, v[162:165] offset:23040
	ds_read_b128 v[178:181], v34 offset:27648
	ds_read_b128 v[224:227], v35 offset:46080
	ds_read_b128 v[182:185], v34 offset:27680
	ds_read_b128 v[200:203], v35 offset:46112
	ds_read_b128 v[248:251], v34 offset:32256
	ds_read_b128 v[186:189], v34 offset:32288
	ds_read_b128 v[208:211], v34 offset:27712
	ds_read_b128 v[230:233], v35 offset:46144
	ds_read_b128 v[166:169], v34 offset:27744
	ds_read_b128 v[190:193], v35 offset:46176
	ds_read_b128 v[194:197], v34 offset:32320
	ds_read_b128 v[170:173], v34 offset:32352
	global_load_dwordx4 v[142:145], v[36:37], off offset:1664
	global_load_dwordx4 v[146:149], v[38:39], off offset:1664
	global_load_dwordx4 v[150:153], v[40:41], off offset:1664
	global_load_dwordx4 v[154:157], v[42:43], off offset:1664
	global_load_dwordx4 v[158:161], v[44:45], off offset:1664
	global_load_dwordx4 v[162:165], v[46:47], off offset:1664
	v_mfma_f32_32x32x16_bf16 v[2:17], v[244:247], v[174:177], v[2:17]
	s_waitcnt lgkmcnt(11)
	s_waitcnt lgkmcnt(10)
	v_mfma_f32_32x32x16_bf16 v[18:33], v[178:181], v[224:227], v[18:33]
	s_waitcnt lgkmcnt(7)
	v_mfma_f32_32x32x16_bf16 v[2:17], v[248:251], v[224:227], v[2:17]
	v_mfma_f32_32x32x16_bf16 v[18:33], v[182:185], v[200:203], v[18:33]
	s_waitcnt lgkmcnt(6)
	v_mfma_f32_32x32x16_bf16 v[2:17], v[186:189], v[200:203], v[2:17]
	s_waitcnt lgkmcnt(5)
	s_waitcnt lgkmcnt(4)
	v_mfma_f32_32x32x16_bf16 v[18:33], v[208:211], v[230:233], v[18:33]
	s_waitcnt lgkmcnt(1)
	v_mfma_f32_32x32x16_bf16 v[2:17], v[194:197], v[230:233], v[2:17]
	v_mfma_f32_32x32x16_bf16 v[18:33], v[166:169], v[190:193], v[18:33]
	s_waitcnt lgkmcnt(0)
	s_barrier
	s_waitcnt vmcnt(5)
	ds_write_b128 v48, v[142:145] offset:27648
	s_waitcnt vmcnt(4)
	ds_write_b128 v48, v[146:149] offset:32256
	s_waitcnt vmcnt(3)
	ds_write_b128 v48, v[150:153] offset:36864
	s_waitcnt vmcnt(2)
	ds_write_b128 v48, v[154:157] offset:41472
	s_waitcnt vmcnt(1)
	ds_write_b128 v48, v[158:161] offset:46080
	s_waitcnt vmcnt(0)
	ds_write_b128 v48, v[162:165] offset:50688
	ds_read_b128 v[236:239], v34
	ds_read_b128 v[204:207], v35 offset:18432
	ds_read_b128 v[244:247], v34 offset:32
	ds_read_b128 v[174:177], v35 offset:18464
	ds_read_b128 v[178:181], v34 offset:4608
	ds_read_b128 v[248:251], v34 offset:4640
	ds_read_b128 v[224:227], v34 offset:64
	ds_read_b128 v[182:185], v35 offset:18496
	ds_read_b128 v[186:189], v34 offset:96
	ds_read_b128 v[200:203], v35 offset:18528
	ds_read_b128 v[208:211], v34 offset:4672
	ds_read_b128 v[194:197], v34 offset:4704
	global_load_dwordx4 v[142:145], v[36:37], off offset:1792
	global_load_dwordx4 v[146:149], v[38:39], off offset:1792
	global_load_dwordx4 v[150:153], v[40:41], off offset:1792
	global_load_dwordx4 v[154:157], v[42:43], off offset:1792
	global_load_dwordx4 v[158:161], v[44:45], off offset:1792
	global_load_dwordx4 v[162:165], v[46:47], off offset:1792
	v_mfma_f32_32x32x16_bf16 v[2:17], v[170:173], v[190:193], v[2:17]
	s_waitcnt lgkmcnt(11)
	s_waitcnt lgkmcnt(10)
	v_mfma_f32_32x32x16_bf16 v[18:33], v[236:239], v[204:207], v[18:33]
	s_waitcnt lgkmcnt(7)
	v_mfma_f32_32x32x16_bf16 v[2:17], v[178:181], v[204:207], v[2:17]
	v_mfma_f32_32x32x16_bf16 v[18:33], v[244:247], v[174:177], v[18:33]
	s_waitcnt lgkmcnt(6)
	v_mfma_f32_32x32x16_bf16 v[2:17], v[248:251], v[174:177], v[2:17]
	s_waitcnt lgkmcnt(5)
	s_waitcnt lgkmcnt(4)
	v_mfma_f32_32x32x16_bf16 v[18:33], v[224:227], v[182:185], v[18:33]
	s_waitcnt lgkmcnt(1)
	v_mfma_f32_32x32x16_bf16 v[2:17], v[208:211], v[182:185], v[2:17]
	v_mfma_f32_32x32x16_bf16 v[18:33], v[186:189], v[200:203], v[18:33]
	s_waitcnt lgkmcnt(0)
	s_barrier
; #define MFMA32(a, b, c) __builtin_amdgcn_mfma_f32_32x32x16_bf16((a), (b), (c), 0, 0, 0)
; #define GEMM_LOADG(kk) { const int ka_ = amode ? (((kk) >> 6) * 96) : (kk); \
;     _Pragma("unroll") for (int i = 0; i < 4; ++i) ra[i] = *(const u32x4*)(A + (size_t)(lr + 32 * i) * lda + ka_ + lk); \
;     _Pragma("unroll") for (int i = 0; i < 2 * NT; ++i) rb[i] = *(const u32x4*)(Bt + (size_t)(lr + 32 * i) * ldb + (kk) + lk); }
; #define GEMM_STORES(buf) { u16* As_ = S + (buf) * TILE; u16* Bs_ = As_ + 128 * LS; \
;     _Pragma("unroll") for (int i = 0; i < 4; ++i) *(u32x4*)(As_ + (lr + 32 * i) * LS + lk) = ra[i]; \
;     _Pragma("unroll") for (int i = 0; i < 2 * NT; ++i) *(u32x4*)(Bs_ + (lr + 32 * i) * LS + lk) = rb[i]; }
; template <int NT>
; DI void gemm_main_np(f32x16 (&acc)[2][NT], const u16* __restrict__ A, int lda, int amode, const u16* __restrict__ Bt,
;                   int ldb, int K, char* smem) {
;     ...
;   for (int k0 = 0; k0 < K; k0 += 64) {
;     const int cur = (k0 >> 6) & 1;
;     if (k0 + 64 < K) {
;       GEMM_STORES(cur ^ 1)
;       if (k0 + 128 < K) GEMM_LOADG(k0 + 128)
;     }
;     const u16* As = S + cur * TILE;
;     const u16* Bs = As + 128 * LS;
; #pragma unroll
;     for (int s = 0; s < 4; ++s) {
;       bf16x8 a[2], b[NT];
; #pragma unroll
;       for (int i = 0; i < 2; ++i) a[i] = *(const bf16x8*)(As + (wm * 64 + i * 32 + l31) * LS + s * 16 + hh * 8);
; #pragma unroll
;       for (int j = 0; j < NT; ++j) b[j] = *(const bf16x8*)(Bs + (wn * 32 * NT + j * 32 + l31) * LS + s * 16 + hh * 8);
; #pragma unroll
;       for (int i = 0; i < 2; ++i)
; #pragma unroll
;         for (int j = 0; j < NT; ++j) acc[i][j] = MFMA32(a[i], b[j], acc[i][j]);
;     }
;     __syncthreads();
; DI void p5_merge_half(KP p, int u, int mt_off, char* smem) {
;     ...
;   for (int br = 0; br < 3; ++br) {
;     f32x16 ag[2][1], ay[2][1];
;     zero_acc(ag[0][0]); zero_acc(ag[1][0]); zero_acc(ay[0][0]); zero_acc(ay[1][0]);
;     gemm_main_np<1>(ag, H, 1024, 0, W + W_ING + (size_t)(br * 1024 + nt * 64) * 1024, 1024, 1024, smem);
;     const u16* A;
;     int lda, amode = 0;
;     if (br == 0) { A = (const u16*)(p->ws + OFF_Q) + (size_t)mt * 128 * 768; lda = 768; amode = 1; }
	s_waitcnt vmcnt(5)
	ds_write_b128 v48, v[142:145]
	s_waitcnt vmcnt(4)
	ds_write_b128 v48, v[146:149] offset:4608
	s_waitcnt vmcnt(3)
	ds_write_b128 v48, v[150:153] offset:9216
	s_waitcnt vmcnt(2)
	ds_write_b128 v48, v[154:157] offset:13824
	s_waitcnt vmcnt(1)
	ds_write_b128 v48, v[158:161] offset:18432
	s_waitcnt vmcnt(0)
	ds_write_b128 v48, v[162:165] offset:23040
	ds_read_b128 v[230:233], v34 offset:27648
	ds_read_b128 v[166:169], v35 offset:46080
	ds_read_b128 v[170:173], v34 offset:27680
	ds_read_b128 v[190:193], v35 offset:46112
	ds_read_b128 v[236:239], v34 offset:32256
	ds_read_b128 v[178:181], v34 offset:32288
	ds_read_b128 v[204:207], v34 offset:27712
	ds_read_b128 v[244:247], v35 offset:46144
	ds_read_b128 v[248:251], v34 offset:27744
	ds_read_b128 v[174:177], v35 offset:46176
	ds_read_b128 v[224:227], v34 offset:32320
	ds_read_b128 v[208:211], v34 offset:32352
	global_load_dwordx4 v[142:145], v[36:37], off offset:1920
	global_load_dwordx4 v[146:149], v[38:39], off offset:1920
	global_load_dwordx4 v[150:153], v[40:41], off offset:1920
	global_load_dwordx4 v[154:157], v[42:43], off offset:1920
	global_load_dwordx4 v[158:161], v[44:45], off offset:1920
	global_load_dwordx4 v[162:165], v[46:47], off offset:1920
	v_mfma_f32_32x32x16_bf16 v[2:17], v[194:197], v[200:203], v[2:17]
	s_waitcnt lgkmcnt(11)
	s_waitcnt lgkmcnt(10)
	v_mfma_f32_32x32x16_bf16 v[18:33], v[230:233], v[166:169], v[18:33]
	s_waitcnt lgkmcnt(7)
	v_mfma_f32_32x32x16_bf16 v[2:17], v[236:239], v[166:169], v[2:17]
	v_mfma_f32_32x32x16_bf16 v[18:33], v[170:173], v[190:193], v[18:33]
	s_waitcnt lgkmcnt(6)
	v_mfma_f32_32x32x16_bf16 v[2:17], v[178:181], v[190:193], v[2:17]
	s_waitcnt lgkmcnt(5)
	s_waitcnt lgkmcnt(4)
	v_mfma_f32_32x32x16_bf16 v[18:33], v[204:207], v[244:247], v[18:33]
	s_waitcnt lgkmcnt(1)
	v_mfma_f32_32x32x16_bf16 v[2:17], v[224:227], v[244:247], v[2:17]
	s_nop 0
	s_nop 0
	s_nop 0
	v_mfma_f32_32x32x16_bf16 v[18:33], v[248:251], v[174:177], v[18:33]
	s_nop 0
	s_waitcnt lgkmcnt(0)
	s_barrier
	s_waitcnt vmcnt(5)
	ds_write_b128 v48, v[142:145] offset:27648
	s_waitcnt vmcnt(4)
	ds_write_b128 v48, v[146:149] offset:32256
	s_waitcnt vmcnt(3)
	ds_write_b128 v48, v[150:153] offset:36864
	s_waitcnt vmcnt(2)
	ds_write_b128 v48, v[154:157] offset:41472
	s_waitcnt vmcnt(1)
	ds_write_b128 v48, v[158:161] offset:46080
	s_waitcnt vmcnt(0)
	ds_write_b128 v48, v[162:165] offset:50688
	ds_read_b128 v[182:185], v34
	ds_read_b128 v[186:189], v35 offset:18432
	ds_read_b128 v[194:197], v34 offset:32
	ds_read_b128 v[200:203], v35 offset:18464
	ds_read_b128 v[230:233], v34 offset:4608
	ds_read_b128 v[236:239], v34 offset:4640
	ds_read_b128 v[166:169], v34 offset:64
	ds_read_b128 v[170:173], v35 offset:18496
	ds_read_b128 v[178:181], v34 offset:96
	ds_read_b128 v[190:193], v35 offset:18528
	ds_read_b128 v[204:207], v34 offset:4672
	ds_read_b128 v[224:227], v34 offset:4704
	v_mfma_f32_32x32x16_bf16 v[2:17], v[208:211], v[174:177], v[2:17]
	s_waitcnt lgkmcnt(11)
	s_waitcnt lgkmcnt(10)
	v_mfma_f32_32x32x16_bf16 v[18:33], v[182:185], v[186:189], v[18:33]
	s_waitcnt lgkmcnt(7)
	v_mfma_f32_32x32x16_bf16 v[2:17], v[230:233], v[186:189], v[2:17]
	v_mfma_f32_32x32x16_bf16 v[18:33], v[194:197], v[200:203], v[18:33]
	s_waitcnt lgkmcnt(6)
	v_mfma_f32_32x32x16_bf16 v[2:17], v[236:239], v[200:203], v[2:17]
	s_waitcnt lgkmcnt(5)
	s_waitcnt lgkmcnt(4)
	v_mfma_f32_32x32x16_bf16 v[18:33], v[166:169], v[170:173], v[18:33]
	s_waitcnt lgkmcnt(0)
	s_barrier
	ds_read_b128 v[244:247], v34 offset:27648
	ds_read_b128 v[248:251], v35 offset:46080
	ds_read_b128 v[208:211], v35 offset:46112
	ds_read_b128 v[174:177], v34 offset:27680
	ds_read_b128 v[182:185], v34 offset:32256
	ds_read_b128 v[230:233], v34 offset:32288
	ds_read_b128 v[186:189], v34 offset:27712
	ds_read_b128 v[194:197], v35 offset:46144
	ds_read_b128 v[236:239], v34 offset:27744
	ds_read_b128 v[200:203], v35 offset:46176
	ds_read_b128 v[166:169], v34 offset:32320
	v_mfma_f32_32x32x16_bf16 v[2:17], v[204:207], v[170:173], v[2:17]
	ds_read_b128 v[204:207], v34 offset:32352
	v_mfma_f32_32x32x16_bf16 v[18:33], v[178:181], v[190:193], v[18:33]
	v_mfma_f32_32x32x16_bf16 v[2:17], v[224:227], v[190:193], v[2:17]
	s_waitcnt lgkmcnt(11)
	s_waitcnt lgkmcnt(10)
	v_mfma_f32_32x32x16_bf16 v[18:33], v[244:247], v[248:251], v[18:33]
	s_waitcnt lgkmcnt(7)
	v_mfma_f32_32x32x16_bf16 v[2:17], v[182:185], v[248:251], v[2:17]
	v_mfma_f32_32x32x16_bf16 v[18:33], v[174:177], v[208:211], v[18:33]
	s_waitcnt lgkmcnt(6)
	v_mfma_f32_32x32x16_bf16 v[2:17], v[230:233], v[208:211], v[2:17]
	s_waitcnt lgkmcnt(5)
	s_waitcnt lgkmcnt(4)
	v_mfma_f32_32x32x16_bf16 v[18:33], v[186:189], v[194:197], v[18:33]
	s_waitcnt lgkmcnt(0)
	s_barrier
	v_mfma_f32_32x32x16_bf16 v[2:17], v[166:169], v[194:197], v[2:17]
	v_mfma_f32_32x32x16_bf16 v[18:33], v[236:239], v[200:203], v[18:33]
	v_mfma_f32_32x32x16_bf16 v[2:17], v[204:207], v[200:203], v[2:17]
	s_cbranch_scc1 .LBB0_1721
	s_cmp_lg_u32 s29, 1
	s_mov_b64 s[18:19], -1
	s_cbranch_scc0 .LBB0_1719
	s_mov_b64 s[18:19], 0
